# attention gather rewrite with the MFMA write-after-write / SrcC write-after-read distances re-derived (7 pads); otherwise version 34
# speedup vs baseline: 1.0038x; 1.0038x over previous
; #define LAS __attribute__((address_space(3)))
; #define ATT_KISSUE(slot_, hg_) do { v2i kx_[4]; \
;             _Pragma("unroll") for (int i = 0; i < 4; ++i) kx_[i] = *(const LAS v2i*)(idl2 + rg * 64 + 16 * i + 2 * (hg_)); \
;             _Pragma("unroll") for (int j = 0; j < 2; ++j) _Pragma("unroll") for (int i = 0; i < 4; ++i) kf[slot_][j][i] = *(const v4u*)(kvb + (size_t)kx_[i][j] * KVD); \
;             ATT_FENCE(); } while (0)
; DI void attn_worker(unsigned char* ws, LAS unsigned char* lds, LAS unsigned* qctr, int wave) {
;     ...
;         f32x4 s[16]; v4u kf[3][2][4];
;     ...
;         ATT_KISSUE(0, 0); ATT_KISSUE(1, 1);
; #pragma unroll
;         for (int hg = 0; hg < 8; ++hg) {
;             if (hg + 2 < 8) ATT_KISSUE((hg + 2) % 3, hg + 2);
; #pragma unroll
;             for (int j = 0; j < 2; ++j) {
; #pragma unroll
;                 for (int i = 0; i < 4; ++i) *(LAS v4u*)(stg + j * 4096 + woff[i]) = kf[hg % 3][j][i];
;                 bf16x8 ka[4];
; #pragma unroll
;                 for (int ks = 0; ks < 4; ++ks) ka[ks] = *(const LAS bf16x8*)(stg + j * 4096 + roff[ks]);
;                 f32x4 a = {0.f, 0.f, 0.f, 0.f};
; #pragma unroll
;                 for (int ks = 0; ks < 4; ++ks) a = __builtin_amdgcn_mfma_f32_16x16x32_bf16(ka[ks], qf[ks], a, 0, 0, 0);
;                 s[2 * hg + j] = a; }
;         }
.LBB0_2280:
	ds_read2_b64 v[16:19], v182 offset0:128 offset1:136
	ds_read2_b64 v[20:23], v182 offset0:144 offset1:152
	s_waitcnt lgkmcnt(1)
	v_lshl_add_u32 v24, v16, 10, v252
	v_lshl_add_u32 v26, v18, 10, v252
	v_mov_b32_e32 v28, v24
	v_mov_b32_e32 v24, v26
	v_mov_b32_e32 v30, v24
	global_load_dwordx4 v[24:27], v28, s[98:99]
	global_load_dwordx4 v[60:63], v30, s[98:99]
	s_waitcnt lgkmcnt(0)
	v_lshl_add_u32 v28, v20, 10, v252
	v_lshl_add_u32 v30, v22, 10, v252
	global_load_dwordx4 v[72:75], v28, s[98:99]
	global_load_dwordx4 v[84:87], v30, s[98:99]
	v_lshl_add_u32 v28, v17, 10, v252
	v_lshl_add_u32 v16, v19, 10, v252
	v_mov_b32_e32 v30, v16
	global_load_dwordx4 v[16:19], v28, s[98:99]
	global_load_dwordx4 v[88:91], v30, s[98:99]
	v_lshl_add_u32 v28, v21, 10, v252
	v_mov_b32_e32 v20, v28
	v_lshl_add_u32 v28, v23, 10, v252
	global_load_dwordx4 v[20:23], v20, s[98:99]
	s_nop 0
	global_load_dwordx4 v[96:99], v28, s[98:99]
	ds_read2_b64 v[28:31], v182 offset0:129 offset1:137
	ds_read2_b64 v[48:51], v182 offset0:145 offset1:153
	s_waitcnt lgkmcnt(1)
	v_lshl_add_u32 v32, v28, 10, v252
	v_lshl_add_u32 v34, v30, 10, v252
	s_waitcnt lgkmcnt(0)
	v_lshl_add_u32 v40, v48, 10, v252
	v_lshl_add_u32 v42, v50, 10, v252
	v_mov_b32_e32 v36, v34
	global_load_dwordx4 v[32:35], v32, s[98:99]
	s_nop 0
	global_load_dwordx4 v[36:39], v36, s[98:99]
	v_mov_b32_e32 v44, v42
	global_load_dwordx4 v[40:43], v40, s[98:99]
	s_nop 0
	global_load_dwordx4 v[80:83], v44, s[98:99]
	v_lshl_add_u32 v44, v29, 10, v252
	v_mov_b32_e32 v28, v44
	v_lshl_add_u32 v44, v31, 10, v252
	v_mov_b32_e32 v30, v44
	global_load_dwordx4 v[44:47], v28, s[98:99]
	global_load_dwordx4 v[68:71], v30, s[98:99]
	v_lshl_add_u32 v28, v49, 10, v252
	v_lshl_add_u32 v30, v51, 10, v252
	global_load_dwordx4 v[100:103], v28, s[98:99]
	global_load_dwordx4 v[108:111], v30, s[98:99]
	ds_read2_b64 v[52:55], v182 offset0:130 offset1:138
	ds_read2_b64 v[92:95], v182 offset0:146 offset1:154
	s_waitcnt lgkmcnt(1)
	v_lshl_add_u32 v28, v52, 10, v252
	v_lshl_add_u32 v30, v54, 10, v252
	s_waitcnt lgkmcnt(0)
	v_lshl_add_u32 v56, v92, 10, v252
	v_lshl_add_u32 v58, v94, 10, v252
	v_mov_b32_e32 v48, v30
	global_load_dwordx4 v[28:31], v28, s[98:99]
	s_nop 0
	global_load_dwordx4 v[48:51], v48, s[98:99]
	global_load_dwordx4 v[64:67], v56, s[98:99]
	global_load_dwordx4 v[76:79], v58, s[98:99]
	v_lshl_add_u32 v56, v53, 10, v252
	v_lshl_add_u32 v104, v93, 10, v252
	v_mov_b32_e32 v52, v56
	v_lshl_add_u32 v56, v55, 10, v252
	v_mov_b32_e32 v92, v104
	v_lshl_add_u32 v104, v95, 10, v252
	global_load_dwordx4 v[52:55], v52, s[98:99]
	s_nop 0
	global_load_dwordx4 v[56:59], v56, s[98:99]
	s_nop 0
	global_load_dwordx4 v[92:95], v92, s[98:99]
	s_nop 0
	global_load_dwordx4 v[104:107], v104, s[98:99]
	s_waitcnt vmcnt(23)
	ds_write_b128 v227, v[24:27] offset:6144
	s_waitcnt vmcnt(22)
	ds_write_b128 v228, v[60:63] offset:6144
	s_waitcnt vmcnt(21)
	ds_write_b128 v229, v[72:75] offset:6144
	s_waitcnt vmcnt(20)
	ds_write_b128 v230, v[84:87] offset:6144
	ds_read_b128 v[24:27], v231 offset:6144
	ds_read_b128 v[60:63], v232 offset:6144
	s_waitcnt lgkmcnt(1)
	v_mfma_f32_16x16x32_bf16 v[24:27], v[24:27], v[4:7], 0
	s_waitcnt lgkmcnt(0)
	v_mfma_f32_16x16x32_bf16 v[24:27], v[60:63], v[0:3], v[24:27]
	ds_read_b128 v[60:63], v233 offset:6144
	ds_read_b128 v[72:75], v234 offset:6144
	s_waitcnt vmcnt(19)
	ds_write_b128 v227, v[16:19] offset:10240
	s_waitcnt vmcnt(18)
	ds_write_b128 v228, v[88:91] offset:10240
	s_waitcnt vmcnt(17)
	ds_write_b128 v229, v[20:23] offset:10240
	s_waitcnt vmcnt(16)
	ds_write_b128 v230, v[96:99] offset:10240
	ds_read_b128 v[16:19], v231 offset:10240
	ds_read_b128 v[20:23], v232 offset:10240
	s_waitcnt lgkmcnt(7)
	v_mfma_f32_16x16x32_bf16 v[24:27], v[60:63], v[12:15], v[24:27]
	ds_read_b128 v[60:63], v233 offset:10240
	s_waitcnt lgkmcnt(2)
	v_mfma_f32_16x16x32_bf16 v[16:19], v[16:19], v[4:7], 0
	v_mfma_f32_16x16x32_bf16 v[24:27], v[72:75], v[8:11], v[24:27]
	ds_read2_b64 v[72:75], v182 offset0:131 offset1:139
	ds_read_b128 v[88:91], v234 offset:10240
	ds_read2_b64 v[116:119], v182 offset0:147 offset1:155
	s_waitcnt lgkmcnt(0)
	v_mfma_f32_16x16x32_bf16 v[16:19], v[20:23], v[0:3], v[16:19]
	v_lshl_add_u32 v120, v117, 10, v252
	v_mfma_f32_16x16x32_bf16 v[112:115], v[60:63], v[12:15], v[16:19]
	v_lshl_add_u32 v60, v116, 10, v252
	s_nop 2
	s_nop 1
	v_lshl_add_u32 v16, v72, 10, v252
	s_nop 0
	v_lshl_add_u32 v18, v74, 10, v252
	v_lshl_add_u32 v62, v118, 10, v252
	v_mov_b32_e32 v20, v18
	global_load_dwordx4 v[16:19], v16, s[98:99]
	s_nop 0
	global_load_dwordx4 v[20:23], v20, s[98:99]
	s_nop 0
	global_load_dwordx4 v[84:87], v60, s[98:99]
	global_load_dwordx4 v[96:99], v62, s[98:99]
	v_lshl_add_u32 v60, v73, 10, v252
	v_lshl_add_u32 v62, v75, 10, v252
	v_mov_b32_e32 v116, v120
	v_lshl_add_u32 v120, v119, 10, v252
	v_mov_b32_e32 v72, v62
	global_load_dwordx4 v[60:63], v60, s[98:99]
	s_nop 0
	global_load_dwordx4 v[72:75], v72, s[98:99]
	global_load_dwordx4 v[116:119], v116, s[98:99]
	s_nop 0
	global_load_dwordx4 v[124:127], v120, s[98:99]
	s_waitcnt vmcnt(23)
	ds_write_b128 v227, v[32:35] offset:6144
	s_waitcnt vmcnt(22)
	ds_write_b128 v228, v[36:39] offset:6144
	s_waitcnt vmcnt(21)
	ds_write_b128 v229, v[40:43] offset:6144
	s_waitcnt vmcnt(20)
	ds_write_b128 v230, v[80:83] offset:6144
	ds_read_b128 v[32:35], v231 offset:6144
	ds_read_b128 v[36:39], v232 offset:6144
	s_waitcnt lgkmcnt(1)
	v_mfma_f32_16x16x32_bf16 v[32:35], v[32:35], v[4:7], 0
	s_waitcnt lgkmcnt(0)
	v_mfma_f32_16x16x32_bf16 v[32:35], v[36:39], v[0:3], v[32:35]
	ds_read_b128 v[36:39], v233 offset:6144
	ds_read_b128 v[80:83], v234 offset:6144
	s_waitcnt vmcnt(19)
; #define LAS __attribute__((address_space(3)))
; #define ATT_KISSUE(slot_, hg_) do { v2i kx_[4]; \
;             _Pragma("unroll") for (int i = 0; i < 4; ++i) kx_[i] = *(const LAS v2i*)(idl2 + rg * 64 + 16 * i + 2 * (hg_)); \
;             _Pragma("unroll") for (int j = 0; j < 2; ++j) _Pragma("unroll") for (int i = 0; i < 4; ++i) kf[slot_][j][i] = *(const v4u*)(kvb + (size_t)kx_[i][j] * KVD); \
;             ATT_FENCE(); } while (0)
; DI void attn_worker(unsigned char* ws, LAS unsigned char* lds, LAS unsigned* qctr, int wave) {
;     ...
;         f32x4 s[16]; v4u kf[3][2][4];
;     ...
;         ATT_KISSUE(0, 0); ATT_KISSUE(1, 1);
; #pragma unroll
;         for (int hg = 0; hg < 8; ++hg) {
;             if (hg + 2 < 8) ATT_KISSUE((hg + 2) % 3, hg + 2);
; #pragma unroll
;             for (int j = 0; j < 2; ++j) {
; #pragma unroll
;                 for (int i = 0; i < 4; ++i) *(LAS v4u*)(stg + j * 4096 + woff[i]) = kf[hg % 3][j][i];
;                 bf16x8 ka[4];
; #pragma unroll
;                 for (int ks = 0; ks < 4; ++ks) ka[ks] = *(const LAS bf16x8*)(stg + j * 4096 + roff[ks]);
;                 f32x4 a = {0.f, 0.f, 0.f, 0.f};
; #pragma unroll
;                 for (int ks = 0; ks < 4; ++ks) a = __builtin_amdgcn_mfma_f32_16x16x32_bf16(ka[ks], qf[ks], a, 0, 0, 0);
;                 s[2 * hg + j] = a; }
;         }
	ds_write_b128 v227, v[44:47] offset:10240
	s_waitcnt vmcnt(18)
	ds_write_b128 v228, v[68:71] offset:10240
	s_waitcnt vmcnt(17)
	ds_write_b128 v229, v[100:103] offset:10240
	s_waitcnt vmcnt(16)
	ds_write_b128 v230, v[108:111] offset:10240
	ds_read_b128 v[68:71], v233 offset:10240
	s_waitcnt lgkmcnt(6)
	v_mfma_f32_16x16x32_bf16 v[32:35], v[36:39], v[12:15], v[32:35]
	ds_read_b128 v[36:39], v231 offset:10240
	s_waitcnt lgkmcnt(6)
	v_mfma_f32_16x16x32_bf16 v[44:47], v[80:83], v[8:11], v[32:35]
	s_nop 4
	ds_read_b128 v[32:35], v232 offset:10240
	s_waitcnt lgkmcnt(1)
	v_mfma_f32_16x16x32_bf16 v[36:39], v[36:39], v[4:7], 0
	ds_read2_b64 v[80:83], v182 offset0:132 offset1:140
	ds_read_b128 v[108:111], v234 offset:10240
	ds_read2_b64 v[120:123], v182 offset0:148 offset1:156
	s_waitcnt lgkmcnt(0)
	v_mfma_f32_16x16x32_bf16 v[32:35], v[32:35], v[0:3], v[36:39]
	v_lshl_add_u32 v128, v121, 10, v252
	v_mfma_f32_16x16x32_bf16 v[40:43], v[88:91], v[8:11], v[112:115]
	v_mfma_f32_16x16x32_bf16 v[112:115], v[68:71], v[12:15], v[32:35]
	v_lshl_add_u32 v68, v120, 10, v252
	s_nop 1
	s_nop 1
	v_lshl_add_u32 v32, v80, 10, v252
	s_nop 0
	v_lshl_add_u32 v34, v82, 10, v252
	v_lshl_add_u32 v70, v122, 10, v252
	v_mov_b32_e32 v36, v34
	global_load_dwordx4 v[32:35], v32, s[98:99]
	s_nop 0
	global_load_dwordx4 v[36:39], v36, s[98:99]
	global_load_dwordx4 v[88:91], v68, s[98:99]
	global_load_dwordx4 v[100:103], v70, s[98:99]
	v_lshl_add_u32 v68, v81, 10, v252
	v_lshl_add_u32 v70, v83, 10, v252
	v_mov_b32_e32 v120, v128
	v_lshl_add_u32 v128, v123, 10, v252
	v_mov_b32_e32 v80, v70
	global_load_dwordx4 v[68:71], v68, s[98:99]
	s_nop 0
	global_load_dwordx4 v[80:83], v80, s[98:99]
	s_nop 0
	global_load_dwordx4 v[120:123], v120, s[98:99]
	s_nop 0
	global_load_dwordx4 v[128:131], v128, s[98:99]
	s_waitcnt vmcnt(23)
	ds_write_b128 v227, v[28:31] offset:6144
	s_waitcnt vmcnt(22)
	ds_write_b128 v228, v[48:51] offset:6144
	s_waitcnt vmcnt(21)
	ds_write_b128 v229, v[64:67] offset:6144
	s_waitcnt vmcnt(20)
	ds_write_b128 v230, v[76:79] offset:6144
	ds_read_b128 v[28:31], v231 offset:6144
	ds_read_b128 v[48:51], v232 offset:6144
	s_waitcnt lgkmcnt(1)
	v_mfma_f32_16x16x32_bf16 v[28:31], v[28:31], v[4:7], 0
	s_waitcnt lgkmcnt(0)
	v_mfma_f32_16x16x32_bf16 v[28:31], v[48:51], v[0:3], v[28:31]
	ds_read_b128 v[48:51], v233 offset:6144
	ds_read_b128 v[64:67], v234 offset:6144
	s_waitcnt vmcnt(19)
	ds_write_b128 v227, v[52:55] offset:10240
	s_waitcnt vmcnt(18)
	ds_write_b128 v228, v[56:59] offset:10240
	s_waitcnt vmcnt(17)
	ds_write_b128 v229, v[92:95] offset:10240
	s_waitcnt vmcnt(16)
	ds_write_b128 v230, v[104:107] offset:10240
	ds_read_b128 v[52:55], v232 offset:10240
	s_waitcnt lgkmcnt(6)
	v_mfma_f32_16x16x32_bf16 v[28:31], v[48:51], v[12:15], v[28:31]
	ds_read_b128 v[48:51], v231 offset:10240
	ds_read_b128 v[56:59], v233 offset:10240
	s_waitcnt lgkmcnt(1)
	v_mfma_f32_16x16x32_bf16 v[48:51], v[48:51], v[4:7], 0
	v_mfma_f32_16x16x32_bf16 v[76:79], v[108:111], v[8:11], v[112:115]
	v_mfma_f32_16x16x32_bf16 v[28:31], v[64:67], v[8:11], v[28:31]
	ds_read2_b64 v[64:67], v182 offset0:133 offset1:141
	ds_read_b128 v[144:147], v234 offset:10240
	ds_read2_b64 v[108:111], v182 offset0:149 offset1:157
	s_waitcnt lgkmcnt(0)
	v_mfma_f32_16x16x32_bf16 v[48:51], v[52:55], v[0:3], v[48:51]
	v_lshl_add_u32 v112, v109, 10, v252
	v_mfma_f32_16x16x32_bf16 v[148:151], v[56:59], v[12:15], v[48:51]
	v_lshl_add_u32 v56, v108, 10, v252
	s_nop 2
	s_nop 1
	v_lshl_add_u32 v48, v64, 10, v252
	s_nop 0
	v_lshl_add_u32 v50, v66, 10, v252
	v_lshl_add_u32 v58, v110, 10, v252
	v_mov_b32_e32 v52, v50
	global_load_dwordx4 v[48:51], v48, s[98:99]
	s_nop 0
	global_load_dwordx4 v[52:55], v52, s[98:99]
	s_nop 0
	global_load_dwordx4 v[92:95], v56, s[98:99]
	global_load_dwordx4 v[104:107], v58, s[98:99]
	v_lshl_add_u32 v56, v65, 10, v252
	v_lshl_add_u32 v58, v67, 10, v252
	v_mov_b32_e32 v108, v112
	v_lshl_add_u32 v112, v111, 10, v252
	v_mov_b32_e32 v64, v58
	global_load_dwordx4 v[56:59], v56, s[98:99]
	s_nop 0
	global_load_dwordx4 v[64:67], v64, s[98:99]
	s_nop 0
	global_load_dwordx4 v[108:111], v108, s[98:99]
	s_nop 0
	global_load_dwordx4 v[112:115], v112, s[98:99]
	s_waitcnt vmcnt(23)
	ds_write_b128 v227, v[16:19] offset:6144
	s_waitcnt vmcnt(22)
	ds_write_b128 v228, v[20:23] offset:6144
	s_waitcnt vmcnt(21)
	ds_write_b128 v229, v[84:87] offset:6144
	s_waitcnt vmcnt(20)
	ds_write_b128 v230, v[96:99] offset:6144
	ds_read_b128 v[20:23], v231 offset:6144
	ds_read_b128 v[84:87], v232 offset:6144
	s_waitcnt lgkmcnt(1)
	v_mfma_f32_16x16x32_bf16 v[20:23], v[20:23], v[4:7], 0
	s_waitcnt lgkmcnt(0)
	v_mfma_f32_16x16x32_bf16 v[20:23], v[84:87], v[0:3], v[20:23]
	ds_read_b128 v[84:87], v233 offset:6144
	ds_read_b128 v[96:99], v234 offset:6144
	s_waitcnt vmcnt(19)
	ds_write_b128 v227, v[60:63] offset:10240
	s_waitcnt vmcnt(18)
	ds_write_b128 v228, v[72:75] offset:10240
	s_waitcnt vmcnt(17)
	ds_write_b128 v229, v[116:119] offset:10240
	s_waitcnt vmcnt(16)
	ds_write_b128 v230, v[124:127] offset:10240
	ds_read_b128 v[60:63], v231 offset:10240
	ds_read_b128 v[72:75], v232 offset:10240
	s_waitcnt lgkmcnt(7)
	v_mfma_f32_16x16x32_bf16 v[20:23], v[84:87], v[12:15], v[20:23]
	ds_read_b128 v[84:87], v233 offset:10240
	s_waitcnt lgkmcnt(7)
	v_mfma_f32_16x16x32_bf16 v[20:23], v[96:99], v[8:11], v[20:23]
	ds_read2_b64 v[96:99], v182 offset0:134 offset1:142
	ds_read_b128 v[116:119], v234 offset:10240
	ds_read2_b64 v[124:127], v182 offset0:150 offset1:158
	s_waitcnt lgkmcnt(2)
	v_mfma_f32_16x16x32_bf16 v[60:63], v[60:63], v[4:7], 0
	v_lshl_add_u32 v152, v97, 10, v252
	s_waitcnt lgkmcnt(0)
; #define LAS __attribute__((address_space(3)))
; #define ATT_KISSUE(slot_, hg_) do { v2i kx_[4]; \
;             _Pragma("unroll") for (int i = 0; i < 4; ++i) kx_[i] = *(const LAS v2i*)(idl2 + rg * 64 + 16 * i + 2 * (hg_)); \
;             _Pragma("unroll") for (int j = 0; j < 2; ++j) _Pragma("unroll") for (int i = 0; i < 4; ++i) kf[slot_][j][i] = *(const v4u*)(kvb + (size_t)kx_[i][j] * KVD); \
;             ATT_FENCE(); } while (0)
; DI void attn_worker(unsigned char* ws, LAS unsigned char* lds, LAS unsigned* qctr, int wave) {
;     ...
;         f32x4 s[16]; v4u kf[3][2][4];
;     ...
;         ATT_KISSUE(0, 0); ATT_KISSUE(1, 1);
; #pragma unroll
;         for (int hg = 0; hg < 8; ++hg) {
;             if (hg + 2 < 8) ATT_KISSUE((hg + 2) % 3, hg + 2);
; #pragma unroll
;             for (int j = 0; j < 2; ++j) {
; #pragma unroll
;                 for (int i = 0; i < 4; ++i) *(LAS v4u*)(stg + j * 4096 + woff[i]) = kf[hg % 3][j][i];
;                 bf16x8 ka[4];
; #pragma unroll
;                 for (int ks = 0; ks < 4; ++ks) ka[ks] = *(const LAS bf16x8*)(stg + j * 4096 + roff[ks]);
;                 f32x4 a = {0.f, 0.f, 0.f, 0.f};
; #pragma unroll
;                 for (int ks = 0; ks < 4; ++ks) a = __builtin_amdgcn_mfma_f32_16x16x32_bf16(ka[ks], qf[ks], a, 0, 0, 0);
;                 s[2 * hg + j] = a; }
;         }
	v_lshl_add_u32 v156, v125, 10, v252
	v_mfma_f32_16x16x32_bf16 v[60:63], v[72:75], v[0:3], v[60:63]
	v_lshl_add_u32 v72, v96, 10, v252
	v_mfma_f32_16x16x32_bf16 v[16:19], v[144:147], v[8:11], v[148:151]
	v_lshl_add_u32 v74, v98, 10, v252
	v_lshl_add_u32 v144, v124, 10, v252
	v_lshl_add_u32 v146, v126, 10, v252
	v_mov_b32_e32 v96, v152
	v_lshl_add_u32 v152, v99, 10, v252
	v_mov_b32_e32 v124, v156
	v_lshl_add_u32 v156, v127, 10, v252
	v_mfma_f32_16x16x32_bf16 v[60:63], v[84:87], v[12:15], v[60:63]
	v_mov_b32_e32 v84, v74
	v_mov_b32_e32 v148, v146
	global_load_dwordx4 v[72:75], v72, s[98:99]
	s_nop 0
	global_load_dwordx4 v[84:87], v84, s[98:99]
	s_nop 0
	global_load_dwordx4 v[144:147], v144, s[98:99]
	s_nop 0
	global_load_dwordx4 v[148:151], v148, s[98:99]
	s_nop 0
	global_load_dwordx4 v[96:99], v96, s[98:99]
	s_nop 0
	global_load_dwordx4 v[152:155], v152, s[98:99]
	s_nop 0
	global_load_dwordx4 v[124:127], v124, s[98:99]
	s_nop 0
	global_load_dwordx4 v[156:159], v156, s[98:99]
	s_waitcnt vmcnt(23)
	ds_write_b128 v227, v[32:35] offset:6144
	s_waitcnt vmcnt(22)
	ds_write_b128 v228, v[36:39] offset:6144
	s_waitcnt vmcnt(21)
	ds_write_b128 v229, v[88:91] offset:6144
	s_waitcnt vmcnt(20)
	ds_write_b128 v230, v[100:103] offset:6144
	ds_read_b128 v[32:35], v231 offset:6144
	v_mfma_f32_16x16x32_bf16 v[36:39], v[116:119], v[8:11], v[60:63]
	s_nop 2
	ds_read_b128 v[60:63], v232 offset:6144
	s_waitcnt lgkmcnt(1)
	v_mfma_f32_16x16x32_bf16 v[32:35], v[32:35], v[4:7], 0
	s_waitcnt lgkmcnt(0)
	v_mfma_f32_16x16x32_bf16 v[32:35], v[60:63], v[0:3], v[32:35]
	ds_read_b128 v[60:63], v233 offset:6144
	ds_read_b128 v[88:91], v234 offset:6144
	s_waitcnt vmcnt(19)
	ds_write_b128 v227, v[68:71] offset:10240
	s_waitcnt vmcnt(18)
	ds_write_b128 v228, v[80:83] offset:10240
	s_waitcnt vmcnt(17)
	ds_write_b128 v229, v[120:123] offset:10240
	s_waitcnt vmcnt(16)
	ds_write_b128 v230, v[128:131] offset:10240
	ds_read_b128 v[68:71], v232 offset:10240
	s_waitcnt lgkmcnt(6)
	v_mfma_f32_16x16x32_bf16 v[32:35], v[60:63], v[12:15], v[32:35]
	ds_read_b128 v[60:63], v231 offset:10240
	ds_read_b128 v[80:83], v233 offset:10240
	s_waitcnt lgkmcnt(1)
	v_mfma_f32_16x16x32_bf16 v[60:63], v[60:63], v[4:7], 0
	v_mfma_f32_16x16x32_bf16 v[60:63], v[68:71], v[0:3], v[60:63]
	v_mfma_f32_16x16x32_bf16 v[32:35], v[88:91], v[8:11], v[32:35]
	ds_read2_b64 v[68:71], v182 offset0:135 offset1:143
	ds_read_b128 v[88:91], v234 offset:10240
	s_waitcnt lgkmcnt(1)
	v_mfma_f32_16x16x32_bf16 v[60:63], v[80:83], v[12:15], v[60:63]
	ds_read2_b64 v[80:83], v182 offset0:151 offset1:159
	v_lshl_add_u32 v100, v68, 10, v252
	v_lshl_add_u32 v102, v70, 10, v252
	s_waitcnt lgkmcnt(0)
	v_lshl_add_u32 v120, v80, 10, v252
	v_lshl_add_u32 v122, v82, 10, v252
	v_mov_b32_e32 v116, v102
	v_mov_b32_e32 v128, v122
	global_load_dwordx4 v[100:103], v100, s[98:99]
	s_nop 0
	global_load_dwordx4 v[116:119], v116, s[98:99]
	s_nop 0
	global_load_dwordx4 v[120:123], v120, s[98:99]
	s_nop 0
	global_load_dwordx4 v[128:131], v128, s[98:99]
	v_lshl_add_u32 v160, v69, 10, v252
	v_lshl_add_u32 v164, v81, 10, v252
	v_mov_b32_e32 v68, v160
	v_lshl_add_u32 v160, v71, 10, v252
	v_mov_b32_e32 v80, v164
	v_lshl_add_u32 v164, v83, 10, v252
	global_load_dwordx4 v[68:71], v68, s[98:99]
	s_nop 0
	global_load_dwordx4 v[160:163], v160, s[98:99]
	s_nop 0
	global_load_dwordx4 v[80:83], v80, s[98:99]
	s_nop 0
	global_load_dwordx4 v[164:167], v164, s[98:99]
	s_waitcnt vmcnt(23)
	ds_write_b128 v227, v[48:51] offset:6144
	s_waitcnt vmcnt(22)
	ds_write_b128 v228, v[52:55] offset:6144
	s_waitcnt vmcnt(21)
	ds_write_b128 v229, v[92:95] offset:6144
	s_waitcnt vmcnt(20)
	ds_write_b128 v230, v[104:107] offset:6144
	ds_read_b128 v[48:51], v231 offset:6144
	ds_read_b128 v[52:55], v232 offset:6144
	s_waitcnt lgkmcnt(1)
	v_mfma_f32_16x16x32_bf16 v[48:51], v[48:51], v[4:7], 0
	v_mfma_f32_16x16x32_bf16 v[60:63], v[88:91], v[8:11], v[60:63]
	s_waitcnt lgkmcnt(0)
	v_mfma_f32_16x16x32_bf16 v[48:51], v[52:55], v[0:3], v[48:51]
	ds_read_b128 v[52:55], v233 offset:6144
	ds_read_b128 v[88:91], v234 offset:6144
	s_waitcnt vmcnt(19)
	ds_write_b128 v227, v[56:59] offset:10240
	s_waitcnt vmcnt(18)
	ds_write_b128 v228, v[64:67] offset:10240
	s_waitcnt vmcnt(17)
	ds_write_b128 v229, v[108:111] offset:10240
	s_waitcnt vmcnt(16)
	ds_write_b128 v230, v[112:115] offset:10240
	ds_read_b128 v[56:59], v231 offset:10240
	s_waitcnt lgkmcnt(6)
	v_mfma_f32_16x16x32_bf16 v[48:51], v[52:55], v[12:15], v[48:51]
	s_waitcnt lgkmcnt(5)
	v_mfma_f32_16x16x32_bf16 v[52:55], v[88:91], v[8:11], v[48:51]
	s_nop 5
	ds_read_b128 v[48:51], v232 offset:10240
	s_waitcnt lgkmcnt(1)
	v_mfma_f32_16x16x32_bf16 v[56:59], v[56:59], v[4:7], 0
	s_waitcnt lgkmcnt(0)
	v_mfma_f32_16x16x32_bf16 v[48:51], v[48:51], v[0:3], v[56:59]
	s_nop 5
	ds_read_b128 v[56:59], v233 offset:10240
	ds_read_b128 v[64:67], v234 offset:10240
	s_waitcnt vmcnt(15)
	ds_write_b128 v227, v[72:75] offset:6144
	s_waitcnt vmcnt(14)
	ds_write_b128 v228, v[84:87] offset:6144
	s_waitcnt vmcnt(13)
	ds_write_b128 v229, v[144:147] offset:6144
	s_waitcnt vmcnt(12)
	ds_write_b128 v230, v[148:151] offset:6144
	s_waitcnt lgkmcnt(5)
	v_mfma_f32_16x16x32_bf16 v[48:51], v[56:59], v[12:15], v[48:51]
	ds_read_b128 v[56:59], v231 offset:6144
	s_waitcnt lgkmcnt(5)
	v_mfma_f32_16x16x32_bf16 v[48:51], v[64:67], v[8:11], v[48:51]
	ds_read_b128 v[64:67], v232 offset:6144
	s_waitcnt lgkmcnt(1)
	v_mfma_f32_16x16x32_bf16 v[56:59], v[56:59], v[4:7], 0
	s_waitcnt lgkmcnt(0)
	v_mfma_f32_16x16x32_bf16 v[56:59], v[64:67], v[0:3], v[56:59]
	ds_read_b128 v[64:67], v233 offset:6144
	ds_read_b128 v[72:75], v234 offset:6144
	s_waitcnt vmcnt(11)
	ds_write_b128 v227, v[96:99] offset:10240
	s_waitcnt vmcnt(10)
; #define LAS __attribute__((address_space(3)))
; #define ATT_FENCE() asm volatile("" ::: "memory")
; #define ATT_KISSUE(slot_, hg_) do { v2i kx_[4]; \
;             _Pragma("unroll") for (int i = 0; i < 4; ++i) kx_[i] = *(const LAS v2i*)(idl2 + rg * 64 + 16 * i + 2 * (hg_)); \
;             _Pragma("unroll") for (int j = 0; j < 2; ++j) _Pragma("unroll") for (int i = 0; i < 4; ++i) kf[slot_][j][i] = *(const v4u*)(kvb + (size_t)kx_[i][j] * KVD); \
;             ATT_FENCE(); } while (0)
; DI void attn_worker(unsigned char* ws, LAS unsigned char* lds, LAS unsigned* qctr, int wave) {
;     ...
;             if (hg + 2 < 8) ATT_KISSUE((hg + 2) % 3, hg + 2);
; #pragma unroll
;             for (int j = 0; j < 2; ++j) {
; #pragma unroll
;                 for (int i = 0; i < 4; ++i) *(LAS v4u*)(stg + j * 4096 + woff[i]) = kf[hg % 3][j][i];
;                 bf16x8 ka[4];
; #pragma unroll
;                 for (int ks = 0; ks < 4; ++ks) ka[ks] = *(const LAS bf16x8*)(stg + j * 4096 + roff[ks]);
;                 f32x4 a = {0.f, 0.f, 0.f, 0.f};
; #pragma unroll
;                 for (int ks = 0; ks < 4; ++ks) a = __builtin_amdgcn_mfma_f32_16x16x32_bf16(ka[ks], qf[ks], a, 0, 0, 0);
;                 s[2 * hg + j] = a; }
;         }
;     ...
;         if (qn2 < SEQ && kr < 4) { const int mq2 = b * SEQ + qn2;
; #pragma unroll
;             for (int ks = 0; ks < 4; ++ks) qf[ks] = *(const bf16x8*)(q + (size_t)mq2 * DA + (4 * g + kr) * 128 + 32 * ks + 8 * kq); }
;         ATT_FENCE();
;         v4i ix[3][2]; v4u vv[3][8];
; #pragma unroll
;         for (int ch = 0; ch < 2; ++ch) {
;             ix[ch][0] = *(const LAS v4i*)(idl + 64 * kg + 8 * ch); ix[ch][1] = *(const LAS v4i*)(idl + 64 * kg + 8 * ch + 4);
; #pragma unroll
;             for (int j = 0; j < 8; ++j) vv[ch][j] = *(const v4u*)(vbase + (size_t)ix[ch][j >> 2][j & 3] * KVD);
;             ATT_FENCE(); }
;         float mx = -3.0e38f;
; #pragma unroll
;         for (int kt = 0; kt < 16; ++kt)
; #pragma unroll
;             for (int e = 0; e < 4; ++e) { const bool ok = (64 * kq + 4 * kt + e) < nvalid; s[kt][e] = ok ? s[kt][e] * 0.08838834764831845f : -3.0e38f; mx = fmaxf(mx, s[kt][e]); }
	ds_write_b128 v228, v[152:155] offset:10240
	s_waitcnt vmcnt(9)
	ds_write_b128 v229, v[124:127] offset:10240
	s_waitcnt vmcnt(8)
	ds_write_b128 v230, v[156:159] offset:10240
	s_waitcnt lgkmcnt(5)
	v_mfma_f32_16x16x32_bf16 v[56:59], v[64:67], v[12:15], v[56:59]
	ds_read_b128 v[64:67], v231 offset:10240
	s_waitcnt lgkmcnt(5)
	v_mfma_f32_16x16x32_bf16 v[56:59], v[72:75], v[8:11], v[56:59]
	ds_read_b128 v[72:75], v232 offset:10240
	s_waitcnt lgkmcnt(1)
	v_mfma_f32_16x16x32_bf16 v[64:67], v[64:67], v[4:7], 0
	s_waitcnt lgkmcnt(0)
	v_mfma_f32_16x16x32_bf16 v[64:67], v[72:75], v[0:3], v[64:67]
	ds_read_b128 v[72:75], v233 offset:10240
	ds_read_b128 v[84:87], v234 offset:10240
	s_waitcnt vmcnt(7)
	ds_write_b128 v227, v[100:103] offset:6144
	s_waitcnt vmcnt(6)
	ds_write_b128 v228, v[116:119] offset:6144
	s_waitcnt vmcnt(5)
	ds_write_b128 v229, v[120:123] offset:6144
	s_waitcnt vmcnt(4)
	ds_write_b128 v230, v[128:131] offset:6144
	s_waitcnt lgkmcnt(5)
	v_mfma_f32_16x16x32_bf16 v[64:67], v[72:75], v[12:15], v[64:67]
	ds_read_b128 v[72:75], v231 offset:6144
	s_waitcnt lgkmcnt(5)
	v_mfma_f32_16x16x32_bf16 v[64:67], v[84:87], v[8:11], v[64:67]
	ds_read_b128 v[84:87], v232 offset:6144
	s_waitcnt lgkmcnt(1)
	v_mfma_f32_16x16x32_bf16 v[72:75], v[72:75], v[4:7], 0
	s_waitcnt lgkmcnt(0)
	v_mfma_f32_16x16x32_bf16 v[72:75], v[84:87], v[0:3], v[72:75]
	ds_read_b128 v[84:87], v233 offset:6144
	ds_read_b128 v[88:91], v234 offset:6144
	s_waitcnt vmcnt(3)
	ds_write_b128 v227, v[68:71] offset:10240
	s_waitcnt vmcnt(2)
	ds_write_b128 v228, v[160:163] offset:10240
	s_waitcnt vmcnt(1)
	ds_write_b128 v229, v[80:83] offset:10240
	s_waitcnt vmcnt(0)
	ds_write_b128 v230, v[164:167] offset:10240
	ds_read_b128 v[68:71], v231 offset:10240
	ds_read_b128 v[80:83], v232 offset:10240
	s_waitcnt lgkmcnt(7)
	v_mfma_f32_16x16x32_bf16 v[72:75], v[84:87], v[12:15], v[72:75]
	ds_read_b128 v[84:87], v233 offset:10240
	s_waitcnt lgkmcnt(2)
	v_mfma_f32_16x16x32_bf16 v[68:71], v[68:71], v[4:7], 0
	s_waitcnt lgkmcnt(1)
	v_mfma_f32_16x16x32_bf16 v[68:71], v[80:83], v[0:3], v[68:71]
	ds_read_b128 v[80:83], v234 offset:10240
	s_waitcnt lgkmcnt(1)
	v_mfma_f32_16x16x32_bf16 v[68:71], v[84:87], v[12:15], v[68:71]
	v_mfma_f32_16x16x32_bf16 v[72:75], v[88:91], v[8:11], v[72:75]
	s_waitcnt lgkmcnt(0)
	v_mfma_f32_16x16x32_bf16 v[68:71], v[80:83], v[8:11], v[68:71]
	s_and_saveexec_b64 s[2:3], s[0:1]
	s_cbranch_execz .LBB0_2282
	v_readlane_b32 s0, v253, 43
	v_readlane_b32 s1, v253, 45
	s_add_i32 s0, s1, s0
	s_ashr_i32 s1, s0, 31
	s_lshl_b64 s[0:1], s[0:1], 12
	v_lshl_add_u64 v[8:9], v[140:141], 0, s[0:1]
	global_load_dwordx4 v[4:7], v[8:9], off
	global_load_dwordx4 v[0:3], v[8:9], off offset:64
	global_load_dwordx4 v[12:15], v[8:9], off offset:128
	s_nop 0
	global_load_dwordx4 v[8:11], v[8:9], off offset:192
.LBB0_2282:
	s_or_b64 exec, exec, s[2:3]
	s_min_i32 s60, s33, 0xff
	v_mul_f32_e32 v80, 0x3db504f3, v24
	v_max_f32_e32 v80, 0xff61b1e6, v80
	v_cmp_lt_i32_e64 s[26:27], s60, v183
	v_mul_f32_e32 v81, 0x3db504f3, v25
	v_cmp_gt_i32_e64 s[34:35], s60, v183
	v_cndmask_b32_e64 v80, v80, v239, s[26:27]
	v_or_b32_e32 v82, 2, v183
	v_cndmask_b32_e64 v81, v239, v81, s[34:35]
	v_or_b32_e32 v83, 3, v183
	v_max_f32_e32 v80, v80, v81
	v_mul_f32_e32 v81, 0x3db504f3, v26
	v_cmp_lt_i32_e64 s[28:29], s60, v82
	v_mul_f32_e32 v82, 0x3db504f3, v27
	v_cmp_lt_i32_e64 s[30:31], s60, v83
	v_cndmask_b32_e64 v81, v81, v239, s[28:29]
	v_or_b32_e32 v83, 5, v183
	v_cndmask_b32_e64 v82, v82, v239, s[30:31]
	v_max3_f32 v80, v80, v81, v82
	v_or_b32_e32 v82, 4, v183
	v_mul_f32_e32 v81, 0x3db504f3, v40
	v_cmp_lt_i32_e64 s[22:23], s60, v82
	v_mul_f32_e32 v82, 0x3db504f3, v41
	v_cmp_lt_i32_e64 s[24:25], s60, v83
	v_cndmask_b32_e64 v81, v81, v239, s[22:23]
	v_or_b32_e32 v83, 7, v183
	v_cndmask_b32_e64 v82, v82, v239, s[24:25]
	v_max3_f32 v80, v80, v81, v82
	v_or_b32_e32 v82, 6, v183
	v_mul_f32_e32 v81, 0x3db504f3, v42
	v_cmp_lt_i32_e64 s[18:19], s60, v82
	v_mul_f32_e32 v82, 0x3db504f3, v43
	v_cmp_lt_i32_e64 s[20:21], s60, v83
	v_cndmask_b32_e64 v81, v81, v239, s[18:19]
	v_or_b32_e32 v83, 9, v183
	v_cndmask_b32_e64 v82, v82, v239, s[20:21]
	v_max3_f32 v80, v80, v81, v82
	v_or_b32_e32 v82, 8, v183
	v_mul_f32_e32 v81, 0x3db504f3, v44
	v_cmp_lt_i32_e64 s[14:15], s60, v82
	v_mul_f32_e32 v82, 0x3db504f3, v45
	v_cmp_lt_i32_e64 s[16:17], s60, v83
	v_cndmask_b32_e64 v81, v81, v239, s[14:15]
	v_or_b32_e32 v83, 11, v183
	v_cndmask_b32_e64 v82, v82, v239, s[16:17]
	v_max3_f32 v80, v80, v81, v82
	v_or_b32_e32 v82, 10, v183
	v_mul_f32_e32 v81, 0x3db504f3, v46
	v_cmp_lt_i32_e64 s[10:11], s60, v82
	v_mul_f32_e32 v82, 0x3db504f3, v47
	v_cmp_lt_i32_e64 s[12:13], s60, v83
	v_cndmask_b32_e64 v81, v81, v239, s[10:11]
	v_or_b32_e32 v83, 13, v183
	v_cndmask_b32_e64 v82, v82, v239, s[12:13]
	v_max3_f32 v80, v80, v81, v82
	v_or_b32_e32 v82, 12, v183
	v_mul_f32_e32 v81, 0x3db504f3, v76
	v_cmp_lt_i32_e64 s[6:7], s60, v82
	v_mul_f32_e32 v82, 0x3db504f3, v77
	v_cmp_lt_i32_e64 s[8:9], s60, v83
	v_cndmask_b32_e64 v81, v81, v239, s[6:7]
	v_or_b32_e32 v83, 15, v183
	v_cndmask_b32_e64 v82, v82, v239, s[8:9]
	v_max3_f32 v80, v80, v81, v82
	v_or_b32_e32 v82, 14, v183
	v_mul_f32_e32 v81, 0x3db504f3, v78
	v_cmp_lt_i32_e64 s[2:3], s60, v82
	v_mul_f32_e32 v82, 0x3db504f3, v79
	v_cmp_lt_i32_e64 s[4:5], s60, v83
	v_cndmask_b32_e64 v81, v81, v239, s[2:3]
	v_or_b32_e32 v83, 17, v183
	v_cndmask_b32_e64 v82, v82, v239, s[4:5]
	v_max3_f32 v80, v80, v81, v82
	v_or_b32_e32 v82, 16, v183
	v_mul_f32_e32 v81, 0x3db504f3, v28
	v_cmp_lt_i32_e32 vcc, s60, v82
	v_mul_f32_e32 v82, 0x3db504f3, v29
	v_cmp_lt_i32_e64 s[0:1], s60, v83
	v_cndmask_b32_e32 v81, v81, v239, vcc
	v_or_b32_e32 v83, 19, v183
; DI void attn_worker(unsigned char* ws, LAS unsigned char* lds, LAS unsigned* qctr, int wave) {
;     ...
;         float mx = -3.0e38f;
; #pragma unroll
;         for (int kt = 0; kt < 16; ++kt)
; #pragma unroll
;             for (int e = 0; e < 4; ++e) { const bool ok = (64 * kq + 4 * kt + e) < nvalid; s[kt][e] = ok ? s[kt][e] * 0.08838834764831845f : -3.0e38f; mx = fmaxf(mx, s[kt][e]); }
;         mx = fmaxf(mx, __shfl_xor(mx, 16)); mx = fmaxf(mx, __shfl_xor(mx, 32));
	v_cndmask_b32_e64 v82, v82, v239, s[0:1]
	v_max3_f32 v80, v80, v81, v82
	v_or_b32_e32 v82, 18, v183
	v_mul_f32_e32 v81, 0x3db504f3, v30
	v_cmp_lt_i32_e64 s[36:37], s60, v82
	v_mul_f32_e32 v82, 0x3db504f3, v31
	v_cmp_lt_i32_e64 s[38:39], s60, v83
	v_cndmask_b32_e64 v81, v81, v239, s[36:37]
	v_cmp_lt_i32_e64 s[56:57], s60, v132
	v_cndmask_b32_e64 v82, v82, v239, s[38:39]
	v_max3_f32 v80, v80, v81, v82
	v_or_b32_e32 v82, 20, v183
	v_mul_f32_e32 v81, 0x3db504f3, v16
	v_cmp_lt_i32_e64 s[96:97], s60, v82
	v_mul_f32_e32 v82, 0x3db504f3, v17
	v_cndmask_b32_e64 v82, v82, v239, s[56:57]
	v_cndmask_b32_e64 v81, v81, v239, s[96:97]
	v_max3_f32 v80, v80, v81, v82
	v_mul_f32_e32 v81, 0x3db504f3, v18
	v_cmp_lt_i32_e64 s[52:53], s60, v185
	v_mul_f32_e32 v82, 0x3db504f3, v19
	v_cmp_lt_i32_e64 s[54:55], s60, v186
	v_cndmask_b32_e64 v81, v81, v239, s[52:53]
	v_cmp_lt_i32_e64 s[48:49], s60, v187
	v_cndmask_b32_e64 v82, v82, v239, s[54:55]
	v_max3_f32 v80, v80, v81, v82
	v_mul_f32_e32 v81, 0x3db504f3, v20
	v_mul_f32_e32 v82, 0x3db504f3, v21
	v_cmp_lt_i32_e64 s[50:51], s60, v188
	v_cndmask_b32_e64 v81, v81, v239, s[48:49]
	v_cmp_lt_i32_e64 s[44:45], s60, v189
	v_cndmask_b32_e64 v82, v82, v239, s[50:51]
	v_max3_f32 v80, v80, v81, v82
	v_mul_f32_e32 v81, 0x3db504f3, v22
	v_mul_f32_e32 v82, 0x3db504f3, v23
	v_cmp_lt_i32_e64 s[46:47], s60, v190
	v_cndmask_b32_e64 v81, v81, v239, s[44:45]
	v_cmp_lt_i32_e64 s[40:41], s60, v191
	v_cndmask_b32_e64 v82, v82, v239, s[46:47]
	v_max3_f32 v80, v80, v81, v82
	v_mul_f32_e32 v81, 0x3db504f3, v36
	v_writelane_b32 v253, s40, 9
	v_mul_f32_e32 v82, 0x3db504f3, v37
	v_cmp_lt_i32_e64 s[42:43], s60, v192
	v_writelane_b32 v253, s41, 10
	v_cndmask_b32_e64 v81, v81, v239, s[40:41]
	v_cndmask_b32_e64 v82, v82, v239, s[42:43]
	v_cmp_lt_i32_e64 s[40:41], s60, v193
	v_max3_f32 v80, v80, v81, v82
	v_mul_f32_e32 v81, 0x3db504f3, v38
	v_writelane_b32 v253, s40, 13
	v_mul_f32_e32 v82, 0x3db504f3, v39
	v_cmp_lt_i32_e64 s[94:95], s60, v208
	v_writelane_b32 v253, s41, 14
	v_cndmask_b32_e64 v81, v81, v239, s[40:41]
	v_cmp_lt_i32_e64 s[40:41], s60, v194
	v_cmp_lt_i32_e64 s[90:91], s60, v209
	v_cmp_lt_i32_e64 s[92:93], s60, v210
	v_writelane_b32 v253, s40, 11
	v_cmp_lt_i32_e64 s[86:87], s60, v211
	v_cmp_lt_i32_e64 s[88:89], s60, v212
	v_writelane_b32 v253, s41, 12
	v_cndmask_b32_e64 v82, v82, v239, s[40:41]
	v_cmp_lt_i32_e64 s[40:41], s60, v195
	v_max3_f32 v80, v80, v81, v82
	v_mul_f32_e32 v81, 0x3db504f3, v32
	v_writelane_b32 v253, s40, 17
	v_mul_f32_e32 v82, 0x3db504f3, v33
	v_cmp_lt_i32_e64 s[82:83], s60, v213
	v_writelane_b32 v253, s41, 18
	v_cndmask_b32_e64 v81, v81, v239, s[40:41]
	v_cmp_lt_i32_e64 s[40:41], s60, v196
	v_cmp_lt_i32_e64 s[84:85], s60, v214
	v_cmp_lt_i32_e64 s[80:81], s60, v216
	v_writelane_b32 v253, s40, 15
	v_cmp_lt_i32_e64 s[74:75], s60, v217
	v_cmp_lt_i32_e64 s[76:77], s60, v218
	v_writelane_b32 v253, s41, 16
	v_cndmask_b32_e64 v82, v82, v239, s[40:41]
	v_cmp_lt_i32_e64 s[40:41], s60, v197
	v_max3_f32 v80, v80, v81, v82
	v_mul_f32_e32 v81, 0x3db504f3, v34
	v_writelane_b32 v253, s40, 21
	v_mul_f32_e32 v82, 0x3db504f3, v35
	v_cmp_lt_i32_e64 s[70:71], s60, v219
	v_writelane_b32 v253, s41, 22
	v_cndmask_b32_e64 v81, v81, v239, s[40:41]
	v_cmp_lt_i32_e64 s[40:41], s60, v198
	v_cmp_lt_i32_e64 s[72:73], s60, v220
	v_and_b32_e32 v84, 64, v235
	v_writelane_b32 v253, s40, 19
	v_cmp_lt_i32_e64 s[66:67], s60, v221
	v_cmp_lt_i32_e64 s[68:69], s60, v222
	v_writelane_b32 v253, s41, 20
	v_cndmask_b32_e64 v82, v82, v239, s[40:41]
	v_cmp_lt_i32_e64 s[40:41], s60, v199
	v_max3_f32 v80, v80, v81, v82
	v_mul_f32_e32 v81, 0x3db504f3, v60
	v_writelane_b32 v253, s40, 25
	v_mul_f32_e32 v82, 0x3db504f3, v61
	v_xor_b32_e32 v83, 16, v235
	v_writelane_b32 v253, s41, 26
	v_cndmask_b32_e64 v81, v81, v239, s[40:41]
	v_cmp_lt_i32_e64 s[40:41], s60, v200
	v_add_u32_e32 v84, 64, v84
	v_cmp_lt_i32_e64 s[58:59], v83, v84
	v_writelane_b32 v253, s40, 23
	v_xor_b32_e32 v85, 32, v235
	v_cmp_lt_i32_e64 s[62:63], s60, v223
	v_writelane_b32 v253, s41, 24
	v_cndmask_b32_e64 v82, v82, v239, s[40:41]
	v_cmp_lt_i32_e64 s[40:41], s60, v201
	v_max3_f32 v80, v80, v81, v82
	v_mul_f32_e32 v81, 0x3db504f3, v62
	v_writelane_b32 v253, s40, 29
	v_mul_f32_e32 v82, 0x3db504f3, v63
	v_cmp_lt_i32_e64 s[64:65], s60, v224
	v_writelane_b32 v253, s41, 30
	v_cndmask_b32_e64 v81, v81, v239, s[40:41]
	v_cmp_lt_i32_e64 s[40:41], s60, v202
	v_cndmask_b32_e64 v83, v235, v83, s[58:59]
	v_cmp_lt_i32_e64 s[58:59], v85, v84
	v_writelane_b32 v253, s40, 27
	v_lshlrev_b32_e32 v241, 2, v83
	v_cndmask_b32_e64 v84, v235, v85, s[58:59]
	v_writelane_b32 v253, s41, 28
	v_cndmask_b32_e64 v82, v82, v239, s[40:41]
	v_cmp_lt_i32_e64 s[40:41], s60, v203
	v_max3_f32 v80, v80, v81, v82
	v_mul_f32_e32 v81, 0x3db504f3, v52
	v_writelane_b32 v253, s40, 33
	v_mul_f32_e32 v82, 0x3db504f3, v53
	v_cmp_lt_i32_e64 s[58:59], s60, v225
	v_writelane_b32 v253, s41, 34
	v_cndmask_b32_e64 v81, v81, v239, s[40:41]
	v_cmp_lt_i32_e64 s[40:41], s60, v204
	v_lshlrev_b32_e32 v240, 2, v84
	s_nop 0
	v_writelane_b32 v253, s40, 31
	s_nop 1
	v_writelane_b32 v253, s41, 32
	v_cndmask_b32_e64 v82, v82, v239, s[40:41]
	v_cmp_lt_i32_e64 s[40:41], s60, v205
	v_max3_f32 v80, v80, v81, v82
	v_mul_f32_e32 v81, 0x3db504f3, v54
	v_writelane_b32 v253, s40, 37
	v_mul_f32_e32 v82, 0x3db504f3, v55
	s_nop 0
	v_writelane_b32 v253, s41, 38
	v_cndmask_b32_e64 v81, v81, v239, s[40:41]
	v_cmp_lt_i32_e64 s[40:41], s60, v206
	s_nop 1
	v_writelane_b32 v253, s40, 35
	s_nop 1
	v_cndmask_b32_e64 v82, v82, v239, s[40:41]
	v_writelane_b32 v253, s41, 36
	v_max3_f32 v80, v80, v81, v82
	v_mul_f32_e32 v81, 0x3db504f3, v48
	v_cmp_lt_i32_e64 s[40:41], s60, v207
; #define LAS __attribute__((address_space(3)))
; DI void attn_worker(unsigned char* ws, LAS unsigned char* lds, LAS unsigned* qctr, int wave) {
;     ...
;             ix[ch][0] = *(const LAS v4i*)(idl + 64 * kg + 8 * ch); ix[ch][1] = *(const LAS v4i*)(idl + 64 * kg + 8 * ch + 4);
;     ...
;             for (int e = 0; e < 4; ++e) { const bool ok = (64 * kq + 4 * kt + e) < nvalid; s[kt][e] = ok ? s[kt][e] * 0.08838834764831845f : -3.0e38f; mx = fmaxf(mx, s[kt][e]); }
;         mx = fmaxf(mx, __shfl_xor(mx, 16)); mx = fmaxf(mx, __shfl_xor(mx, 32));
;         float sum = 0.f;
; #pragma unroll
;         for (int kt = 0; kt < 16; ++kt)
; #pragma unroll
;             for (int e = 0; e < 4; ++e) { const bool ok = (64 * kq + 4 * kt + e) < nvalid; const float p = ok ? __expf(s[kt][e] - mx) : 0.f; s[kt][e] = p; sum += p; }
;         sum += __shfl_xor(sum, 16); sum += __shfl_xor(sum, 32);
	v_mul_f32_e32 v82, 0x3db504f3, v49
	v_cndmask_b32_e64 v82, v82, v239, s[94:95]
	v_writelane_b32 v253, s40, 39
	s_nop 1
	v_cndmask_b32_e64 v81, v81, v239, s[40:41]
	v_max3_f32 v80, v80, v81, v82
	v_mul_f32_e32 v81, 0x3db504f3, v50
	v_mul_f32_e32 v82, 0x3db504f3, v51
	v_cndmask_b32_e64 v81, v81, v239, s[90:91]
	v_cndmask_b32_e64 v82, v82, v239, s[92:93]
	v_max3_f32 v80, v80, v81, v82
	v_mul_f32_e32 v81, 0x3db504f3, v56
	v_mul_f32_e32 v82, 0x3db504f3, v57
	v_cndmask_b32_e64 v81, v81, v239, s[86:87]
	v_cndmask_b32_e64 v82, v82, v239, s[88:89]
	v_max3_f32 v80, v80, v81, v82
	v_mul_f32_e32 v81, 0x3db504f3, v58
	v_mul_f32_e32 v82, 0x3db504f3, v59
	v_cndmask_b32_e64 v81, v81, v239, s[82:83]
	v_cndmask_b32_e64 v82, v82, v239, s[84:85]
	v_writelane_b32 v253, s41, 40
	v_max3_f32 v80, v80, v81, v82
	v_mul_f32_e32 v81, 0x3db504f3, v64
	v_cmp_lt_i32_e64 s[40:41], s60, v215
	v_mul_f32_e32 v82, 0x3db504f3, v65
	v_cndmask_b32_e64 v82, v82, v239, s[80:81]
	v_cndmask_b32_e64 v81, v81, v239, s[40:41]
	v_max3_f32 v80, v80, v81, v82
	v_mul_f32_e32 v81, 0x3db504f3, v66
	v_mul_f32_e32 v82, 0x3db504f3, v67
	v_cndmask_b32_e64 v81, v81, v239, s[74:75]
	v_cndmask_b32_e64 v82, v82, v239, s[76:77]
	v_max3_f32 v80, v80, v81, v82
	v_mul_f32_e32 v81, 0x3db504f3, v72
	v_mul_f32_e32 v82, 0x3db504f3, v73
	v_cndmask_b32_e64 v81, v81, v239, s[70:71]
	v_cndmask_b32_e64 v82, v82, v239, s[72:73]
	v_max3_f32 v80, v80, v81, v82
	v_mul_f32_e32 v81, 0x3db504f3, v74
	v_mul_f32_e32 v82, 0x3db504f3, v75
	v_cndmask_b32_e64 v81, v81, v239, s[66:67]
	v_cndmask_b32_e64 v82, v82, v239, s[68:69]
	v_max3_f32 v80, v80, v81, v82
	v_mul_f32_e32 v81, 0x3db504f3, v68
	v_mul_f32_e32 v82, 0x3db504f3, v69
	v_cndmask_b32_e64 v81, v81, v239, s[62:63]
	v_cndmask_b32_e64 v82, v82, v239, s[64:65]
	v_max3_f32 v80, v80, v81, v82
	v_mul_f32_e32 v81, 0x3db504f3, v70
	v_mul_f32_e32 v82, 0x3db504f3, v71
	v_cmp_lt_i32_e64 s[60:61], s60, v226
	v_cndmask_b32_e64 v81, v81, v239, s[58:59]
	s_nop 0
	v_cndmask_b32_e64 v82, v82, v239, s[60:61]
	v_max3_f32 v80, v80, v81, v82
	ds_bpermute_b32 v81, v241, v80
	s_waitcnt lgkmcnt(0)
	v_max_f32_e32 v81, v81, v81
	v_max_f32_e32 v80, v80, v81
	ds_bpermute_b32 v81, v240, v80
	s_waitcnt lgkmcnt(0)
	v_max_f32_e32 v81, v81, v81
	v_max_f32_e32 v242, v80, v81
	v_fma_f32 v24, v24, s78, -v242
	v_mul_f32_e32 v24, 0x3fb8aa3b, v24
	v_exp_f32_e32 v24, v24
	v_fma_f32 v30, v30, s78, -v242
	v_mul_f32_e32 v30, 0x3fb8aa3b, v30
	v_fma_f32 v31, v31, s78, -v242
	v_cndmask_b32_e64 v124, v24, 0, s[26:27]
	v_fma_f32 v24, v25, s78, -v242
	v_mul_f32_e32 v24, 0x3fb8aa3b, v24
	v_exp_f32_e32 v24, v24
	v_exp_f32_e32 v30, v30
	v_mul_f32_e32 v31, 0x3fb8aa3b, v31
	v_fma_f32 v16, v16, s78, -v242
	v_cndmask_b32_e64 v125, 0, v24, s[34:35]
	v_fma_f32 v24, v26, s78, -v242
	v_mul_f32_e32 v24, 0x3fb8aa3b, v24
	v_exp_f32_e32 v24, v24
	v_exp_f32_e32 v31, v31
	v_mul_f32_e32 v16, 0x3fb8aa3b, v16
	v_fma_f32 v17, v17, s78, -v242
	v_cndmask_b32_e64 v128, v24, 0, s[28:29]
	v_fma_f32 v24, v27, s78, -v242
	v_mul_f32_e32 v24, 0x3fb8aa3b, v24
	v_exp_f32_e32 v24, v24
	v_exp_f32_e32 v16, v16
	v_mul_f32_e32 v17, 0x3fb8aa3b, v17
	v_fma_f32 v18, v18, s78, -v242
	v_cndmask_b32_e64 v129, v24, 0, s[30:31]
	v_fma_f32 v24, v40, s78, -v242
	v_mul_f32_e32 v24, 0x3fb8aa3b, v24
	v_exp_f32_e32 v24, v24
	v_exp_f32_e32 v17, v17
	v_mul_f32_e32 v18, 0x3fb8aa3b, v18
	v_fma_f32 v19, v19, s78, -v242
	v_cndmask_b32_e64 v130, v24, 0, s[22:23]
	v_fma_f32 v24, v41, s78, -v242
	v_mul_f32_e32 v24, 0x3fb8aa3b, v24
	v_exp_f32_e32 v24, v24
	v_cndmask_b32_e64 v30, v30, 0, s[36:37]
	v_exp_f32_e32 v18, v18
	v_mul_f32_e32 v19, 0x3fb8aa3b, v19
	v_cndmask_b32_e64 v131, v24, 0, s[24:25]
	v_fma_f32 v24, v42, s78, -v242
	v_mul_f32_e32 v24, 0x3fb8aa3b, v24
	v_exp_f32_e32 v24, v24
	v_cndmask_b32_e64 v31, v31, 0, s[38:39]
	v_exp_f32_e32 v19, v19
	v_cndmask_b32_e64 v16, v16, 0, s[96:97]
	v_cndmask_b32_e64 v148, v24, 0, s[18:19]
	v_fma_f32 v24, v43, s78, -v242
	v_mul_f32_e32 v24, 0x3fb8aa3b, v24
	v_exp_f32_e32 v24, v24
	v_cndmask_b32_e64 v17, v17, 0, s[56:57]
	v_fma_f32 v32, v32, s78, -v242
	v_mul_f32_e32 v32, 0x3fb8aa3b, v32
	v_cndmask_b32_e64 v149, v24, 0, s[20:21]
	v_fma_f32 v24, v44, s78, -v242
	v_mul_f32_e32 v24, 0x3fb8aa3b, v24
	v_exp_f32_e32 v24, v24
	v_exp_f32_e32 v32, v32
	v_fma_f32 v33, v33, s78, -v242
	v_mul_f32_e32 v33, 0x3fb8aa3b, v33
	v_cndmask_b32_e64 v126, v24, 0, s[14:15]
	v_fma_f32 v24, v45, s78, -v242
	v_mul_f32_e32 v24, 0x3fb8aa3b, v24
	v_exp_f32_e32 v24, v24
	v_exp_f32_e32 v33, v33
	v_fma_f32 v34, v34, s78, -v242
	v_mul_f32_e32 v34, 0x3fb8aa3b, v34
	v_cndmask_b32_e64 v127, v24, 0, s[16:17]
	v_fma_f32 v24, v46, s78, -v242
	v_mul_f32_e32 v24, 0x3fb8aa3b, v24
	v_exp_f32_e32 v24, v24
	v_exp_f32_e32 v34, v34
	v_fma_f32 v35, v35, s78, -v242
	v_mul_f32_e32 v35, 0x3fb8aa3b, v35
	v_cndmask_b32_e64 v144, v24, 0, s[10:11]
	v_fma_f32 v24, v47, s78, -v242
	v_mul_f32_e32 v24, 0x3fb8aa3b, v24
	v_exp_f32_e32 v24, v24
	v_exp_f32_e32 v35, v35
	v_cndmask_b32_e64 v145, v24, 0, s[12:13]
	v_fma_f32 v24, v76, s78, -v242
	v_mul_f32_e32 v24, 0x3fb8aa3b, v24
	v_exp_f32_e32 v24, v24
	s_nop 0
	v_cndmask_b32_e64 v146, v24, 0, s[6:7]
	v_fma_f32 v24, v77, s78, -v242
	v_mul_f32_e32 v24, 0x3fb8aa3b, v24
	v_exp_f32_e32 v24, v24
	s_nop 0
	v_cndmask_b32_e64 v147, v24, 0, s[8:9]
	v_fma_f32 v24, v78, s78, -v242
	v_mul_f32_e32 v24, 0x3fb8aa3b, v24
	v_exp_f32_e32 v24, v24
	s_nop 0
	v_cndmask_b32_e64 v150, v24, 0, s[2:3]
	v_fma_f32 v24, v79, s78, -v242
	v_mul_f32_e32 v24, 0x3fb8aa3b, v24
	v_exp_f32_e32 v24, v24
	s_nop 0
	v_cndmask_b32_e64 v151, v24, 0, s[4:5]
	v_fma_f32 v24, v28, s78, -v242
	v_mul_f32_e32 v24, 0x3fb8aa3b, v24
	v_exp_f32_e32 v24, v24
	s_nop 0
	v_cndmask_b32_e64 v28, v24, 0, vcc
	v_fma_f32 v24, v29, s78, -v242
	v_mul_f32_e32 v24, 0x3fb8aa3b, v24
	v_exp_f32_e32 v24, v24
	s_nop 0
	v_cndmask_b32_e64 v29, v24, 0, s[0:1]
	ds_read_b128 v[24:27], v182
	ds_read_b128 v[40:43], v182 offset:16
	v_readlane_b32 s0, v253, 9
	v_readlane_b32 s1, v253, 10
	s_waitcnt lgkmcnt(1)
; #define LAS __attribute__((address_space(3)))
; #define ATT_FENCE() asm volatile("" ::: "memory")
; DI void attn_worker(unsigned char* ws, LAS unsigned char* lds, LAS unsigned* qctr, int wave) {
;     ...
;             ix[ch][0] = *(const LAS v4i*)(idl + 64 * kg + 8 * ch); ix[ch][1] = *(const LAS v4i*)(idl + 64 * kg + 8 * ch + 4);
; #pragma unroll
;             for (int j = 0; j < 8; ++j) vv[ch][j] = *(const v4u*)(vbase + (size_t)ix[ch][j >> 2][j & 3] * KVD);
;             ATT_FENCE(); }
;         float mx = -3.0e38f;
; #pragma unroll
;         for (int kt = 0; kt < 16; ++kt)
; #pragma unroll
;             for (int e = 0; e < 4; ++e) { const bool ok = (64 * kq + 4 * kt + e) < nvalid; s[kt][e] = ok ? s[kt][e] * 0.08838834764831845f : -3.0e38f; mx = fmaxf(mx, s[kt][e]); }
;         mx = fmaxf(mx, __shfl_xor(mx, 16)); mx = fmaxf(mx, __shfl_xor(mx, 32));
;         float sum = 0.f;
; #pragma unroll
;         for (int kt = 0; kt < 16; ++kt)
; #pragma unroll
;             for (int e = 0; e < 4; ++e) { const bool ok = (64 * kq + 4 * kt + e) < nvalid; const float p = ok ? __expf(s[kt][e] - mx) : 0.f; s[kt][e] = p; sum += p; }
;         sum += __shfl_xor(sum, 16); sum += __shfl_xor(sum, 32);
	v_lshl_add_u32 v44, v24, 10, v252
	v_lshl_add_u32 v46, v25, 10, v252
	global_load_dwordx4 v[88:91], v44, s[100:101]
	global_load_dwordx4 v[92:95], v46, s[100:101]
	v_lshl_add_u32 v24, v26, 10, v252
	v_lshl_add_u32 v44, v27, 10, v252
	global_load_dwordx4 v[96:99], v24, s[100:101]
	global_load_dwordx4 v[100:103], v44, s[100:101]
	s_waitcnt lgkmcnt(0)
	v_lshl_add_u32 v24, v40, 10, v252
	v_lshl_add_u32 v26, v41, 10, v252
	global_load_dwordx4 v[104:107], v24, s[100:101]
	global_load_dwordx4 v[108:111], v26, s[100:101]
	v_lshl_add_u32 v24, v42, 10, v252
	v_lshl_add_u32 v26, v43, 10, v252
	global_load_dwordx4 v[112:115], v24, s[100:101]
	global_load_dwordx4 v[116:119], v26, s[100:101]
	ds_read_b128 v[42:45], v182 offset:32
	ds_read_b128 v[120:123], v182 offset:48
	s_waitcnt lgkmcnt(1)
	s_waitcnt lgkmcnt(0)
	v_lshl_add_u32 v80, v120, 10, v252
	v_add_f32_e32 v120, 0, v124
	v_add_f32_e32 v120, v125, v120
	v_add_f32_e32 v120, v128, v120
	v_add_f32_e32 v120, v129, v120
	v_add_f32_e32 v120, v130, v120
	v_add_f32_e32 v120, v131, v120
	v_add_f32_e32 v120, v148, v120
	v_add_f32_e32 v120, v149, v120
	v_add_f32_e32 v120, v126, v120
	v_add_f32_e32 v120, v127, v120
	v_add_f32_e32 v120, v144, v120
	v_add_f32_e32 v120, v145, v120
	v_add_f32_e32 v120, v146, v120
	v_add_f32_e32 v120, v147, v120
	v_add_f32_e32 v120, v150, v120
	v_add_f32_e32 v120, v151, v120
	v_add_f32_e32 v120, v28, v120
	v_add_f32_e32 v120, v29, v120
	v_add_f32_e32 v120, v30, v120
	v_add_f32_e32 v120, v31, v120
	v_add_f32_e32 v120, v16, v120
	v_lshl_add_u32 v82, v121, 10, v252
	v_add_f32_e32 v121, v17, v120
	v_cndmask_b32_e64 v120, v18, 0, s[52:53]
	v_add_f32_e32 v18, v120, v121
	v_cndmask_b32_e64 v121, v19, 0, s[54:55]
	v_fma_f32 v19, v20, s78, -v242
	v_fma_f32 v20, v21, s78, -v242
	v_mul_f32_e32 v19, 0x3fb8aa3b, v19
	v_mul_f32_e32 v20, 0x3fb8aa3b, v20
	v_exp_f32_e32 v19, v19
	v_exp_f32_e32 v20, v20
	v_add_f32_e32 v21, v121, v18
	v_lshl_add_u32 v24, v42, 10, v252
	v_cndmask_b32_e64 v18, v19, 0, s[48:49]
	v_cndmask_b32_e64 v19, v20, 0, s[50:51]
	v_fma_f32 v20, v22, s78, -v242
	v_mul_f32_e32 v20, 0x3fb8aa3b, v20
	v_fma_f32 v22, v23, s78, -v242
	v_exp_f32_e32 v20, v20
	v_mul_f32_e32 v22, 0x3fb8aa3b, v22
	v_exp_f32_e32 v22, v22
	v_add_f32_e32 v21, v18, v21
	v_add_f32_e32 v21, v19, v21
	v_cndmask_b32_e64 v20, v20, 0, s[44:45]
	v_add_f32_e32 v23, v20, v21
	v_cndmask_b32_e64 v21, v22, 0, s[46:47]
	v_fma_f32 v22, v36, s78, -v242
	v_mul_f32_e32 v22, 0x3fb8aa3b, v22
	v_fma_f32 v36, v37, s78, -v242
	v_exp_f32_e32 v22, v22
	v_mul_f32_e32 v36, 0x3fb8aa3b, v36
	v_exp_f32_e32 v36, v36
	v_add_f32_e32 v23, v21, v23
	v_cndmask_b32_e64 v22, v22, 0, s[0:1]
	v_add_f32_e32 v37, v22, v23
	v_cndmask_b32_e64 v23, v36, 0, s[42:43]
	v_fma_f32 v36, v38, s78, -v242
	v_mul_f32_e32 v36, 0x3fb8aa3b, v36
	v_exp_f32_e32 v36, v36
	v_fma_f32 v38, v39, s78, -v242
	v_mul_f32_e32 v38, 0x3fb8aa3b, v38
	v_exp_f32_e32 v38, v38
	v_readlane_b32 s0, v253, 13
	v_readlane_b32 s1, v253, 14
	v_add_f32_e32 v37, v23, v37
	s_nop 0
	v_cndmask_b32_e64 v36, v36, 0, s[0:1]
	v_readlane_b32 s0, v253, 11
	v_readlane_b32 s1, v253, 12
	v_add_f32_e32 v39, v36, v37
	v_lshl_add_u32 v26, v43, 10, v252
	v_cndmask_b32_e64 v37, v38, 0, s[0:1]
	v_readlane_b32 s0, v253, 17
	v_readlane_b32 s1, v253, 18
	v_add_f32_e32 v38, v37, v39
	v_fma_f32 v39, v60, s78, -v242
	v_cndmask_b32_e64 v32, v32, 0, s[0:1]
	v_readlane_b32 s0, v253, 15
	v_readlane_b32 s1, v253, 16
	v_mul_f32_e32 v39, 0x3fb8aa3b, v39
	v_exp_f32_e32 v39, v39
	v_cndmask_b32_e64 v33, v33, 0, s[0:1]
	v_readlane_b32 s0, v253, 21
	v_readlane_b32 s1, v253, 22
	v_fma_f32 v60, v61, s78, -v242
	v_mul_f32_e32 v60, 0x3fb8aa3b, v60
	v_cndmask_b32_e64 v34, v34, 0, s[0:1]
	v_readlane_b32 s0, v253, 19
	v_readlane_b32 s1, v253, 20
	v_exp_f32_e32 v60, v60
	v_add_f32_e32 v38, v32, v38
	v_cndmask_b32_e64 v35, v35, 0, s[0:1]
	v_readlane_b32 s0, v253, 25
	v_readlane_b32 s1, v253, 26
	v_add_f32_e32 v38, v33, v38
	v_add_f32_e32 v38, v34, v38
	v_cndmask_b32_e64 v152, v39, 0, s[0:1]
	v_fma_f32 v39, v62, s78, -v242
	v_mul_f32_e32 v39, 0x3fb8aa3b, v39
	v_readlane_b32 s0, v253, 23
	v_exp_f32_e32 v39, v39
	v_readlane_b32 s1, v253, 24
	v_add_f32_e32 v38, v35, v38
	v_add_f32_e32 v38, v152, v38
	v_cndmask_b32_e64 v153, v60, 0, s[0:1]
	v_fma_f32 v60, v63, s78, -v242
	v_readlane_b32 s0, v253, 29
	v_mul_f32_e32 v60, 0x3fb8aa3b, v60
	v_readlane_b32 s1, v253, 30
	v_exp_f32_e32 v60, v60
	v_add_f32_e32 v38, v153, v38
	v_cndmask_b32_e64 v156, v39, 0, s[0:1]
	v_fma_f32 v39, v52, s78, -v242
	v_mul_f32_e32 v39, 0x3fb8aa3b, v39
	v_readlane_b32 s0, v253, 27
	v_exp_f32_e32 v39, v39
	v_readlane_b32 s1, v253, 28
	v_fma_f32 v52, v53, s78, -v242
	v_mul_f32_e32 v52, 0x3fb8aa3b, v52
	v_cndmask_b32_e64 v157, v60, 0, s[0:1]
	v_readlane_b32 s0, v253, 33
	v_readlane_b32 s1, v253, 34
	v_exp_f32_e32 v52, v52
	v_add_f32_e32 v38, v156, v38
	v_cndmask_b32_e64 v154, v39, 0, s[0:1]
	v_fma_f32 v39, v54, s78, -v242
	v_mul_f32_e32 v39, 0x3fb8aa3b, v39
	v_readlane_b32 s0, v253, 31
	v_exp_f32_e32 v39, v39
	v_readlane_b32 s1, v253, 32
	v_add_f32_e32 v38, v157, v38
	v_add_f32_e32 v38, v154, v38
	v_cndmask_b32_e64 v155, v52, 0, s[0:1]
	v_fma_f32 v52, v55, s78, -v242
	v_readlane_b32 s0, v253, 37
	v_mul_f32_e32 v52, 0x3fb8aa3b, v52
	v_readlane_b32 s1, v253, 38
	v_exp_f32_e32 v52, v52
	v_add_f32_e32 v38, v155, v38
	v_cndmask_b32_e64 v158, v39, 0, s[0:1]
	v_fma_f32 v39, v48, s78, -v242
	v_mul_f32_e32 v39, 0x3fb8aa3b, v39
	v_fma_f32 v48, v49, s78, -v242
	v_readlane_b32 s0, v253, 35
	v_exp_f32_e32 v39, v39
	v_mul_f32_e32 v48, 0x3fb8aa3b, v48
	v_readlane_b32 s1, v253, 36
	v_exp_f32_e32 v48, v48
	v_add_f32_e32 v38, v158, v38
	v_cndmask_b32_e64 v159, v52, 0, s[0:1]
; #define LAS __attribute__((address_space(3)))
; DI v4u pack8(const f4& a, const f4& b) { v4u w; w.x = cvt_pk_bf16(a[0], a[1]); w.y = cvt_pk_bf16(a[2], a[3]); w.z = cvt_pk_bf16(b[0], b[1]); w.w = cvt_pk_bf16(b[2], b[3]); return w; }
; DI void attn_worker(unsigned char* ws, LAS unsigned char* lds, LAS unsigned* qctr, int wave) {
;     ...
;         float sum = 0.f;
; #pragma unroll
;         for (int kt = 0; kt < 16; ++kt)
; #pragma unroll
;             for (int e = 0; e < 4; ++e) { const bool ok = (64 * kq + 4 * kt + e) < nvalid; const float p = ok ? __expf(s[kt][e] - mx) : 0.f; s[kt][e] = p; sum += p; }
;         sum += __shfl_xor(sum, 16); sum += __shfl_xor(sum, 32);
;         const float inv = 1.0f / sum;
;         bf16x8 pa[8];
; #pragma unroll
;         for (int sg = 0; sg < 8; ++sg) pa[sg] = __builtin_bit_cast(bf16x8, epi::pack8(s[2 * sg] * inv, s[2 * sg + 1] * inv));
;     ...
;             if (ch + 2 < 8) { const int c2 = (ch + 2) % 3;
;                 ix[c2][0] = *(const LAS v4i*)(idl + 64 * kg + 8 * (ch + 2)); ix[c2][1] = *(const LAS v4i*)(idl + 64 * kg + 8 * (ch + 2) + 4);
; #pragma unroll
;                 for (int j = 0; j < 8; ++j) vv[c2][j] = *(const v4u*)(vbase + (size_t)ix[c2][j >> 2][j & 3] * KVD);
	v_readlane_b32 s0, v253, 39
	v_readlane_b32 s1, v253, 40
	v_cndmask_b32_e64 v161, v48, 0, s[94:95]
	v_fma_f32 v48, v51, s78, -v242
	v_cndmask_b32_e64 v160, v39, 0, s[0:1]
	v_fma_f32 v39, v50, s78, -v242
	v_mul_f32_e32 v39, 0x3fb8aa3b, v39
	v_exp_f32_e32 v39, v39
	v_mul_f32_e32 v48, 0x3fb8aa3b, v48
	v_exp_f32_e32 v48, v48
	v_add_f32_e32 v38, v159, v38
	v_cndmask_b32_e64 v164, v39, 0, s[90:91]
	v_fma_f32 v39, v56, s78, -v242
	v_cndmask_b32_e64 v165, v48, 0, s[92:93]
	v_mul_f32_e32 v39, 0x3fb8aa3b, v39
	v_fma_f32 v48, v57, s78, -v242
	v_exp_f32_e32 v39, v39
	v_mul_f32_e32 v48, 0x3fb8aa3b, v48
	v_exp_f32_e32 v48, v48
	v_add_f32_e32 v38, v160, v38
	v_cndmask_b32_e64 v162, v39, 0, s[86:87]
	v_fma_f32 v39, v58, s78, -v242
	v_cndmask_b32_e64 v163, v48, 0, s[88:89]
	v_mul_f32_e32 v39, 0x3fb8aa3b, v39
	v_fma_f32 v48, v59, s78, -v242
	v_exp_f32_e32 v39, v39
	v_mul_f32_e32 v48, 0x3fb8aa3b, v48
	v_exp_f32_e32 v48, v48
	v_add_f32_e32 v38, v161, v38
	v_cndmask_b32_e64 v166, v39, 0, s[82:83]
	v_fma_f32 v39, v64, s78, -v242
	v_cndmask_b32_e64 v167, v48, 0, s[84:85]
	v_mul_f32_e32 v39, 0x3fb8aa3b, v39
	v_fma_f32 v48, v65, s78, -v242
	v_exp_f32_e32 v39, v39
	v_mul_f32_e32 v48, 0x3fb8aa3b, v48
	v_exp_f32_e32 v48, v48
	v_add_f32_e32 v38, v164, v38
	v_cndmask_b32_e64 v168, v39, 0, s[40:41]
	v_fma_f32 v39, v66, s78, -v242
	v_cndmask_b32_e64 v169, v48, 0, s[80:81]
	v_mul_f32_e32 v39, 0x3fb8aa3b, v39
	v_fma_f32 v48, v67, s78, -v242
	v_exp_f32_e32 v39, v39
	v_mul_f32_e32 v48, 0x3fb8aa3b, v48
	v_exp_f32_e32 v48, v48
	v_add_f32_e32 v38, v165, v38
	v_cndmask_b32_e64 v170, v39, 0, s[74:75]
	v_fma_f32 v39, v72, s78, -v242
	v_cndmask_b32_e64 v171, v48, 0, s[76:77]
	v_mul_f32_e32 v39, 0x3fb8aa3b, v39
	v_fma_f32 v48, v73, s78, -v242
	v_exp_f32_e32 v39, v39
	v_mul_f32_e32 v48, 0x3fb8aa3b, v48
	v_exp_f32_e32 v48, v48
	v_add_f32_e32 v38, v162, v38
	v_cndmask_b32_e64 v72, v39, 0, s[70:71]
	v_fma_f32 v39, v74, s78, -v242
	v_cndmask_b32_e64 v73, v48, 0, s[72:73]
	v_mul_f32_e32 v39, 0x3fb8aa3b, v39
	v_fma_f32 v48, v75, s78, -v242
	v_exp_f32_e32 v39, v39
	v_mul_f32_e32 v48, 0x3fb8aa3b, v48
	v_exp_f32_e32 v48, v48
	v_add_f32_e32 v38, v163, v38
	v_cndmask_b32_e64 v74, v39, 0, s[66:67]
	v_fma_f32 v39, v68, s78, -v242
	v_add_f32_e32 v38, v166, v38
	v_cndmask_b32_e64 v75, v48, 0, s[68:69]
	v_mul_f32_e32 v39, 0x3fb8aa3b, v39
	v_fma_f32 v48, v69, s78, -v242
	v_add_f32_e32 v38, v167, v38
	v_exp_f32_e32 v39, v39
	v_mul_f32_e32 v48, 0x3fb8aa3b, v48
	v_add_f32_e32 v38, v168, v38
	v_exp_f32_e32 v48, v48
	v_add_f32_e32 v38, v169, v38
	v_add_f32_e32 v38, v170, v38
	v_add_f32_e32 v38, v171, v38
	v_cndmask_b32_e64 v68, v39, 0, s[62:63]
	v_fma_f32 v39, v70, s78, -v242
	v_add_f32_e32 v38, v72, v38
	v_cndmask_b32_e64 v69, v48, 0, s[64:65]
	v_mul_f32_e32 v39, 0x3fb8aa3b, v39
	v_fma_f32 v48, v71, s78, -v242
	v_add_f32_e32 v38, v73, v38
	v_exp_f32_e32 v39, v39
	v_mul_f32_e32 v48, 0x3fb8aa3b, v48
	v_add_f32_e32 v38, v74, v38
	v_exp_f32_e32 v48, v48
	v_add_f32_e32 v38, v75, v38
	v_add_f32_e32 v38, v68, v38
	v_add_f32_e32 v38, v69, v38
	v_cndmask_b32_e64 v70, v39, 0, s[58:59]
	v_add_f32_e32 v38, v70, v38
	v_cndmask_b32_e64 v71, v48, 0, s[60:61]
	v_add_f32_e32 v48, v71, v38
	ds_bpermute_b32 v49, v241, v48
	v_lshl_add_u32 v46, v44, 10, v252
	v_lshl_add_u32 v76, v45, 10, v252
	v_lshl_add_u32 v38, v122, 10, v252
	s_waitcnt lgkmcnt(0)
	v_add_f32_e32 v50, v48, v49
	v_lshl_add_u32 v48, v123, 10, v252
	v_mov_b32_e32 v40, v26
	v_mov_b32_e32 v84, v82
	global_load_dwordx4 v[24:27], v24, s[100:101]
	s_nop 0
	global_load_dwordx4 v[40:43], v40, s[100:101]
	s_nop 0
	global_load_dwordx4 v[44:47], v46, s[100:101]
	s_nop 0
	global_load_dwordx4 v[76:79], v76, s[100:101]
	s_nop 0
	global_load_dwordx4 v[80:83], v80, s[100:101]
	s_nop 0
	global_load_dwordx4 v[84:87], v84, s[100:101]
	global_load_dwordx4 v[52:55], v38, s[100:101]
	global_load_dwordx4 v[56:59], v48, s[100:101]
	ds_bpermute_b32 v51, v240, v50
	s_waitcnt lgkmcnt(0)
	v_add_f32_e32 v50, v50, v51
	v_div_scale_f32 v51, s[0:1], v50, v50, 1.0
	v_rcp_f32_e32 v60, v51
	s_nop 0
	v_fma_f32 v38, -v51, v60, 1.0
	v_fmac_f32_e32 v60, v38, v60
	v_div_scale_f32 v38, vcc, 1.0, v50, 1.0
	v_mul_f32_e32 v39, v38, v60
	v_fma_f32 v48, -v51, v39, v38
	v_fmac_f32_e32 v39, v48, v60
	v_fma_f32 v38, -v51, v39, v38
	v_div_fmas_f32 v38, v38, v60, v39
	v_div_fixup_f32 v122, v38, v50, 1.0
	v_pk_mul_f32 v[48:49], v[124:125], v[122:123] op_sel_hi:[1,0]
	v_pk_mul_f32 v[50:51], v[148:149], v[122:123] op_sel_hi:[1,0]
	v_pk_mul_f32 v[38:39], v[128:129], v[122:123] op_sel_hi:[1,0]
	v_pk_mul_f32 v[60:61], v[130:131], v[122:123] op_sel_hi:[1,0]
	v_cvt_pk_bf16_f32 v64, v48, v49
	v_cvt_pk_bf16_f32 v65, v38, v39
	v_pk_mul_f32 v[48:49], v[126:127], v[122:123] op_sel_hi:[1,0]
	v_cvt_pk_bf16_f32 v66, v60, v61
	v_cvt_pk_bf16_f32 v67, v50, v51
	v_pk_mul_f32 v[50:51], v[150:151], v[122:123] op_sel_hi:[1,0]
	v_pk_mul_f32 v[62:63], v[146:147], v[122:123] op_sel_hi:[1,0]
	v_pk_mul_f32 v[16:17], v[16:17], v[122:123] op_sel_hi:[1,0]
	v_pk_mul_f32 v[38:39], v[144:145], v[122:123] op_sel_hi:[1,0]
	v_cvt_pk_bf16_f32 v60, v48, v49
	v_pk_mul_f32 v[30:31], v[30:31], v[122:123] op_sel_hi:[1,0]
	v_cvt_pk_bf16_f32 v61, v38, v39
	v_cvt_pk_bf16_f32 v62, v62, v63
	v_cvt_pk_bf16_f32 v63, v50, v51
	v_pk_mul_f32 v[28:29], v[28:29], v[122:123] op_sel_hi:[1,0]
	v_pk_mul_f32 v[18:19], v[18:19], v[122:123] op_sel_hi:[1,0]
	v_cvt_pk_bf16_f32 v48, v28, v29
	v_cvt_pk_bf16_f32 v49, v30, v31
	v_cvt_pk_bf16_f32 v50, v16, v17
	v_pk_mul_f32 v[16:17], v[20:21], v[122:123] op_sel_hi:[1,0]
	v_pk_mul_f32 v[38:39], v[120:121], v[122:123] op_sel_hi:[1,0]
	v_pk_mul_f32 v[20:21], v[36:37], v[122:123] op_sel_hi:[1,0]
	v_cvt_pk_bf16_f32 v51, v38, v39
; #define LAS __attribute__((address_space(3)))
; #define ATT_FENCE() asm volatile("" ::: "memory")
; DI void attn_worker(unsigned char* ws, LAS unsigned char* lds, LAS unsigned* qctr, int wave) {
;     ...
;         for (int sg = 0; sg < 8; ++sg) pa[sg] = __builtin_bit_cast(bf16x8, epi::pack8(s[2 * sg] * inv, s[2 * sg + 1] * inv));
;         f32x4 acc[8];
; #pragma unroll
;         for (int nt = 0; nt < 8; ++nt) acc[nt] = (f32x4){0.f, 0.f, 0.f, 0.f};
; #pragma unroll
;         for (int ch = 0; ch < 8; ++ch) {
;             if (ch + 2 < 8) { const int c2 = (ch + 2) % 3;
;                 ix[c2][0] = *(const LAS v4i*)(idl + 64 * kg + 8 * (ch + 2)); ix[c2][1] = *(const LAS v4i*)(idl + 64 * kg + 8 * (ch + 2) + 4);
; #pragma unroll
;                 for (int j = 0; j < 8; ++j) vv[c2][j] = *(const v4u*)(vbase + (size_t)ix[c2][j >> 2][j & 3] * KVD);
;                 ATT_FENCE(); }
; #pragma unroll
;             for (int j = 0; j < 8; ++j) *(LAS v4u*)(size_t)(vwb[j >> 2] + 64 * j) = vv[ch % 3][j];
;             v2u r0, r1, r2, r3, r4, r5, r6, r7, r8, r9, r10, r11, r12, r13, r14, r15;
;             asm volatile("ds_read_b64_tr_b16 %0, %16\n\tds_read_b64_tr_b16 %1, %18\n\tds_read_b64_tr_b16 %2, %17\n\tds_read_b64_tr_b16 %3, %19\n\t"
;                          "ds_read_b64_tr_b16 %4, %16 offset:512\n\tds_read_b64_tr_b16 %5, %18 offset:512\n\tds_read_b64_tr_b16 %6, %17 offset:512\n\tds_read_b64_tr_b16 %7, %19 offset:512\n\t"
;                          "ds_read_b64_tr_b16 %8, %16 offset:1024\n\tds_read_b64_tr_b16 %9, %18 offset:1024\n\tds_read_b64_tr_b16 %10, %17 offset:1024\n\tds_read_b64_tr_b16 %11, %19 offset:1024\n\t"
;                          "ds_read_b64_tr_b16 %12, %16 offset:1536\n\tds_read_b64_tr_b16 %13, %18 offset:1536\n\tds_read_b64_tr_b16 %14, %17 offset:1536\n\tds_read_b64_tr_b16 %15, %19 offset:1536\n\ts_waitcnt lgkmcnt(0)"
;                          : "=&v"(r0), "=&v"(r1), "=&v"(r2), "=&v"(r3), "=&v"(r4), "=&v"(r5), "=&v"(r6), "=&v"(r7), "=&v"(r8), "=&v"(r9), "=&v"(r10), "=&v"(r11), "=&v"(r12), "=&v"(r13), "=&v"(r14), "=&v"(r15)
;                          : "v"(vtb[0][0]), "v"(vtb[0][1]), "v"(vtb[1][0]), "v"(vtb[1][1]) : "memory");
;     ...
;             ATT_PV(0, r0, r1); ATT_PV(1, r2, r3); ATT_PV(2, r4, r5); ATT_PV(3, r6, r7); ATT_PV(4, r8, r9); ATT_PV(5, r10, r11); ATT_PV(6, r12, r13); ATT_PV(7, r14, r15);
	v_pk_mul_f32 v[22:23], v[22:23], v[122:123] op_sel_hi:[1,0]
	v_cvt_pk_bf16_f32 v36, v18, v19
	v_cvt_pk_bf16_f32 v37, v16, v17
	v_pk_mul_f32 v[16:17], v[34:35], v[122:123] op_sel_hi:[1,0]
	v_pk_mul_f32 v[18:19], v[32:33], v[122:123] op_sel_hi:[1,0]
	v_cvt_pk_bf16_f32 v38, v22, v23
	v_cvt_pk_bf16_f32 v39, v20, v21
	v_pk_mul_f32 v[20:21], v[156:157], v[122:123] op_sel_hi:[1,0]
	v_pk_mul_f32 v[22:23], v[152:153], v[122:123] op_sel_hi:[1,0]
	v_cvt_pk_bf16_f32 v32, v18, v19
	v_cvt_pk_bf16_f32 v33, v16, v17
	v_pk_mul_f32 v[16:17], v[158:159], v[122:123] op_sel_hi:[1,0]
	v_pk_mul_f32 v[18:19], v[154:155], v[122:123] op_sel_hi:[1,0]
	v_cvt_pk_bf16_f32 v34, v22, v23
	v_cvt_pk_bf16_f32 v35, v20, v21
	v_pk_mul_f32 v[20:21], v[164:165], v[122:123] op_sel_hi:[1,0]
	v_pk_mul_f32 v[22:23], v[160:161], v[122:123] op_sel_hi:[1,0]
	v_cvt_pk_bf16_f32 v28, v18, v19
	v_cvt_pk_bf16_f32 v29, v16, v17
	v_pk_mul_f32 v[16:17], v[166:167], v[122:123] op_sel_hi:[1,0]
	v_pk_mul_f32 v[18:19], v[162:163], v[122:123] op_sel_hi:[1,0]
	v_cvt_pk_bf16_f32 v30, v22, v23
	v_cvt_pk_bf16_f32 v31, v20, v21
	v_pk_mul_f32 v[120:121], v[170:171], v[122:123] op_sel_hi:[1,0]
	v_pk_mul_f32 v[22:23], v[168:169], v[122:123] op_sel_hi:[1,0]
	v_cvt_pk_bf16_f32 v20, v18, v19
	v_cvt_pk_bf16_f32 v21, v16, v17
	v_pk_mul_f32 v[18:19], v[74:75], v[122:123] op_sel_hi:[1,0]
	v_pk_mul_f32 v[16:17], v[72:73], v[122:123] op_sel_hi:[1,0]
	v_cvt_pk_bf16_f32 v22, v22, v23
	v_cvt_pk_bf16_f32 v23, v120, v121
	v_pk_mul_f32 v[70:71], v[70:71], v[122:123] op_sel_hi:[1,0]
	v_pk_mul_f32 v[68:69], v[68:69], v[122:123] op_sel_hi:[1,0]
	v_cvt_pk_bf16_f32 v16, v16, v17
	v_cvt_pk_bf16_f32 v17, v18, v19
	s_nop 0
	v_cvt_pk_bf16_f32 v18, v68, v69
	v_cvt_pk_bf16_f32 v19, v70, v71
	ds_read_b128 v[120:123], v182 offset:64
	ds_read_b128 v[124:127], v182 offset:80
	s_waitcnt lgkmcnt(1)
	v_lshl_add_u32 v68, v120, 10, v252
	v_lshl_add_u32 v70, v121, 10, v252
	v_lshl_add_u32 v120, v122, 10, v252
	v_lshl_add_u32 v128, v123, 10, v252
	s_waitcnt lgkmcnt(0)
	v_lshl_add_u32 v144, v124, 10, v252
	v_lshl_add_u32 v146, v125, 10, v252
	v_mov_b32_e32 v124, v146
	v_mov_b32_e32 v72, v70
	global_load_dwordx4 v[68:71], v68, s[100:101]
	s_nop 0
	global_load_dwordx4 v[72:75], v72, s[100:101]
	s_nop 0
	global_load_dwordx4 v[120:123], v120, s[100:101]
	s_nop 0
	global_load_dwordx4 v[128:131], v128, s[100:101]
	s_nop 0
	global_load_dwordx4 v[144:147], v144, s[100:101]
	s_nop 0
	global_load_dwordx4 v[148:151], v124, s[100:101]
	v_lshl_add_u32 v124, v126, 10, v252
	v_lshl_add_u32 v152, v127, 10, v252
	global_load_dwordx4 v[124:127], v124, s[100:101]
	s_nop 0
	global_load_dwordx4 v[152:155], v152, s[100:101]
	s_waitcnt vmcnt(23)
	ds_write_b128 v236, v[88:91]
	s_waitcnt vmcnt(22)
	ds_write_b128 v236, v[92:95] offset:64
	s_waitcnt vmcnt(21)
	ds_write_b128 v236, v[96:99] offset:128
	s_waitcnt vmcnt(20)
	ds_write_b128 v236, v[100:103] offset:192
	s_waitcnt vmcnt(19)
	ds_write_b128 v237, v[104:107] offset:256
	s_waitcnt vmcnt(18)
	ds_write_b128 v237, v[108:111] offset:320
	s_waitcnt vmcnt(17)
	ds_write_b128 v237, v[112:115] offset:384
	s_waitcnt vmcnt(16)
	ds_write_b128 v237, v[116:119] offset:448
	ds_read_b64_tr_b16 v[116:117], v176
	ds_read_b64_tr_b16 v[118:119], v178
	ds_read_b64_tr_b16 v[112:113], v177
	ds_read_b64_tr_b16 v[114:115], v179
	ds_read_b64_tr_b16 v[108:109], v176 offset:512
	ds_read_b64_tr_b16 v[110:111], v178 offset:512
	ds_read_b64_tr_b16 v[104:105], v177 offset:512
	ds_read_b64_tr_b16 v[106:107], v179 offset:512
	ds_read_b64_tr_b16 v[100:101], v176 offset:1024
	ds_read_b64_tr_b16 v[102:103], v178 offset:1024
	ds_read_b64_tr_b16 v[96:97], v177 offset:1024
	ds_read_b64_tr_b16 v[98:99], v179 offset:1024
	ds_read_b64_tr_b16 v[92:93], v176 offset:1536
	ds_read_b64_tr_b16 v[94:95], v178 offset:1536
	ds_read_b64_tr_b16 v[88:89], v177 offset:1536
	ds_read_b64_tr_b16 v[90:91], v179 offset:1536
	s_waitcnt lgkmcnt(0)
	ds_read_b128 v[156:159], v182 offset:96
	ds_read_b128 v[164:167], v182 offset:112
	v_mfma_f32_16x16x32_bf16 v[116:119], v[64:67], v[116:119], 0
	s_waitcnt lgkmcnt(1)
	v_mfma_f32_16x16x32_bf16 v[112:115], v[64:67], v[112:115], 0
	v_lshl_add_u32 v168, v159, 10, v252
	s_waitcnt lgkmcnt(0)
	v_lshl_add_u32 v240, v164, 10, v252
	v_mfma_f32_16x16x32_bf16 v[108:111], v[64:67], v[108:111], 0
	v_lshl_add_u32 v242, v165, 10, v252
	v_mfma_f32_16x16x32_bf16 v[104:107], v[64:67], v[104:107], 0
	v_mov_b32_e32 v164, v242
	v_mfma_f32_16x16x32_bf16 v[100:103], v[64:67], v[100:103], 0
	v_lshl_add_u32 v248, v167, 10, v252
	v_mfma_f32_16x16x32_bf16 v[96:99], v[64:67], v[96:99], 0
	v_mfma_f32_16x16x32_bf16 v[92:95], v[64:67], v[92:95], 0
	v_mfma_f32_16x16x32_bf16 v[160:163], v[64:67], v[88:91], 0
	v_lshl_add_u32 v64, v156, 10, v252
	v_lshl_add_u32 v66, v157, 10, v252
	v_lshl_add_u32 v156, v158, 10, v252
	v_mov_b32_e32 v88, v66
	global_load_dwordx4 v[64:67], v64, s[100:101]
	s_nop 0
	global_load_dwordx4 v[88:91], v88, s[100:101]
	s_nop 0
	global_load_dwordx4 v[156:159], v156, s[100:101]
	s_nop 0
	global_load_dwordx4 v[168:171], v168, s[100:101]
	s_nop 0
	global_load_dwordx4 v[240:243], v240, s[100:101]
	s_nop 0
	global_load_dwordx4 v[244:247], v164, s[100:101]
	v_lshl_add_u32 v164, v166, 10, v252
	global_load_dwordx4 v[164:167], v164, s[100:101]
	s_nop 0
	global_load_dwordx4 v[248:251], v248, s[100:101]
	s_waitcnt vmcnt(23)
	ds_write_b128 v236, v[24:27]
	s_waitcnt vmcnt(22)
	ds_write_b128 v236, v[40:43] offset:64
	s_waitcnt vmcnt(21)
	ds_write_b128 v236, v[44:47] offset:128
	s_waitcnt vmcnt(20)
	ds_write_b128 v236, v[76:79] offset:192
	s_waitcnt vmcnt(19)
	ds_write_b128 v237, v[80:83] offset:256
	s_waitcnt vmcnt(18)
	ds_write_b128 v237, v[84:87] offset:320
	s_waitcnt vmcnt(17)
; #define LAS __attribute__((address_space(3)))
; #define ATT_FENCE() asm volatile("" ::: "memory")
; #define ATT_PV(nt_, ra_, rb_) acc[nt_] = __builtin_amdgcn_mfma_f32_16x16x32_bf16(pa[ch], __builtin_bit_cast(bf16x8, (v4u){ra_.x, ra_.y, rb_.x, rb_.y}), acc[nt_], 0, 0, 0)
; DI void attn_worker(unsigned char* ws, LAS unsigned char* lds, LAS unsigned* qctr, int wave) {
;     ...
;         for (int ch = 0; ch < 8; ++ch) {
;             if (ch + 2 < 8) { const int c2 = (ch + 2) % 3;
;                 ix[c2][0] = *(const LAS v4i*)(idl + 64 * kg + 8 * (ch + 2)); ix[c2][1] = *(const LAS v4i*)(idl + 64 * kg + 8 * (ch + 2) + 4);
; #pragma unroll
;                 for (int j = 0; j < 8; ++j) vv[c2][j] = *(const v4u*)(vbase + (size_t)ix[c2][j >> 2][j & 3] * KVD);
;                 ATT_FENCE(); }
; #pragma unroll
;             for (int j = 0; j < 8; ++j) *(LAS v4u*)(size_t)(vwb[j >> 2] + 64 * j) = vv[ch % 3][j];
;             v2u r0, r1, r2, r3, r4, r5, r6, r7, r8, r9, r10, r11, r12, r13, r14, r15;
;             asm volatile("ds_read_b64_tr_b16 %0, %16\n\tds_read_b64_tr_b16 %1, %18\n\tds_read_b64_tr_b16 %2, %17\n\tds_read_b64_tr_b16 %3, %19\n\t"
;                          "ds_read_b64_tr_b16 %4, %16 offset:512\n\tds_read_b64_tr_b16 %5, %18 offset:512\n\tds_read_b64_tr_b16 %6, %17 offset:512\n\tds_read_b64_tr_b16 %7, %19 offset:512\n\t"
;                          "ds_read_b64_tr_b16 %8, %16 offset:1024\n\tds_read_b64_tr_b16 %9, %18 offset:1024\n\tds_read_b64_tr_b16 %10, %17 offset:1024\n\tds_read_b64_tr_b16 %11, %19 offset:1024\n\t"
;                          "ds_read_b64_tr_b16 %12, %16 offset:1536\n\tds_read_b64_tr_b16 %13, %18 offset:1536\n\tds_read_b64_tr_b16 %14, %17 offset:1536\n\tds_read_b64_tr_b16 %15, %19 offset:1536\n\ts_waitcnt lgkmcnt(0)"
;                          : "=&v"(r0), "=&v"(r1), "=&v"(r2), "=&v"(r3), "=&v"(r4), "=&v"(r5), "=&v"(r6), "=&v"(r7), "=&v"(r8), "=&v"(r9), "=&v"(r10), "=&v"(r11), "=&v"(r12), "=&v"(r13), "=&v"(r14), "=&v"(r15)
;                          : "v"(vtb[0][0]), "v"(vtb[0][1]), "v"(vtb[1][0]), "v"(vtb[1][1]) : "memory");
;     ...
;             ATT_PV(0, r0, r1); ATT_PV(1, r2, r3); ATT_PV(2, r4, r5); ATT_PV(3, r6, r7); ATT_PV(4, r8, r9); ATT_PV(5, r10, r11); ATT_PV(6, r12, r13); ATT_PV(7, r14, r15);
	ds_write_b128 v237, v[52:55] offset:384
	s_waitcnt vmcnt(16)
	ds_write_b128 v237, v[56:59] offset:448
	ds_read_b64_tr_b16 v[84:85], v176
	ds_read_b64_tr_b16 v[86:87], v178
	ds_read_b64_tr_b16 v[80:81], v177
	ds_read_b64_tr_b16 v[82:83], v179
	ds_read_b64_tr_b16 v[76:77], v176 offset:512
	ds_read_b64_tr_b16 v[78:79], v178 offset:512
	ds_read_b64_tr_b16 v[56:57], v177 offset:512
	ds_read_b64_tr_b16 v[58:59], v179 offset:512
	ds_read_b64_tr_b16 v[52:53], v176 offset:1024
	ds_read_b64_tr_b16 v[54:55], v178 offset:1024
	ds_read_b64_tr_b16 v[44:45], v177 offset:1024
	ds_read_b64_tr_b16 v[46:47], v179 offset:1024
	ds_read_b64_tr_b16 v[40:41], v176 offset:1536
	ds_read_b64_tr_b16 v[42:43], v178 offset:1536
	ds_read_b64_tr_b16 v[24:25], v177 offset:1536
	ds_read_b64_tr_b16 v[26:27], v179 offset:1536
	s_waitcnt lgkmcnt(0)
	s_nop 0
	v_mfma_f32_16x16x32_bf16 v[52:55], v[60:63], v[52:55], v[100:103]
	v_mfma_f32_16x16x32_bf16 v[44:47], v[60:63], v[44:47], v[96:99]
	s_nop 1
	ds_read_b128 v[100:103], v182 offset:144
	ds_read_b128 v[96:99], v182 offset:128
	v_mfma_f32_16x16x32_bf16 v[84:87], v[60:63], v[84:87], v[116:119]
	v_mfma_f32_16x16x32_bf16 v[80:83], v[60:63], v[80:83], v[112:115]
	s_waitcnt lgkmcnt(1)
	s_nop 0
	v_lshl_add_u32 v116, v103, 10, v252
	v_mfma_f32_16x16x32_bf16 v[76:79], v[60:63], v[76:79], v[108:111]
	v_mfma_f32_16x16x32_bf16 v[56:59], v[60:63], v[56:59], v[104:107]
	s_nop 1
	v_lshl_add_u32 v108, v100, 10, v252
	v_mfma_f32_16x16x32_bf16 v[92:95], v[60:63], v[40:43], v[92:95]
	s_waitcnt lgkmcnt(0)
	v_lshl_add_u32 v104, v99, 10, v252
	v_lshl_add_u32 v110, v101, 10, v252
	v_mfma_f32_16x16x32_bf16 v[60:63], v[60:63], v[24:27], v[160:163]
	v_lshl_add_u32 v24, v96, 10, v252
	v_lshl_add_u32 v26, v97, 10, v252
	v_lshl_add_u32 v96, v98, 10, v252
	v_mov_b32_e32 v100, v110
	v_mov_b32_e32 v40, v26
	global_load_dwordx4 v[24:27], v24, s[100:101]
	s_nop 0
	global_load_dwordx4 v[40:43], v40, s[100:101]
	s_nop 0
	global_load_dwordx4 v[96:99], v96, s[100:101]
	s_nop 0
	global_load_dwordx4 v[104:107], v104, s[100:101]
	s_nop 0
	global_load_dwordx4 v[108:111], v108, s[100:101]
	s_nop 0
	global_load_dwordx4 v[112:115], v100, s[100:101]
	v_lshl_add_u32 v100, v102, 10, v252
	global_load_dwordx4 v[100:103], v100, s[100:101]
	s_nop 0
	global_load_dwordx4 v[116:119], v116, s[100:101]
	s_waitcnt vmcnt(23)
	ds_write_b128 v236, v[68:71]
	s_waitcnt vmcnt(22)
	ds_write_b128 v236, v[72:75] offset:64
	s_waitcnt vmcnt(21)
	ds_write_b128 v236, v[120:123] offset:128
	s_waitcnt vmcnt(20)
	ds_write_b128 v236, v[128:131] offset:192
	s_waitcnt vmcnt(19)
	ds_write_b128 v237, v[144:147] offset:256
	s_waitcnt vmcnt(18)
	ds_write_b128 v237, v[148:151] offset:320
	s_waitcnt vmcnt(17)
	ds_write_b128 v237, v[124:127] offset:384
	s_waitcnt vmcnt(16)
	ds_write_b128 v237, v[152:155] offset:448
	ds_read_b64_tr_b16 v[152:153], v176
	ds_read_b64_tr_b16 v[154:155], v178
	ds_read_b64_tr_b16 v[148:149], v177
	ds_read_b64_tr_b16 v[150:151], v179
	ds_read_b64_tr_b16 v[144:145], v176 offset:512
	ds_read_b64_tr_b16 v[146:147], v178 offset:512
	ds_read_b64_tr_b16 v[128:129], v177 offset:512
	ds_read_b64_tr_b16 v[130:131], v179 offset:512
	ds_read_b64_tr_b16 v[124:125], v176 offset:1024
	ds_read_b64_tr_b16 v[126:127], v178 offset:1024
	ds_read_b64_tr_b16 v[120:121], v177 offset:1024
	ds_read_b64_tr_b16 v[122:123], v179 offset:1024
	ds_read_b64_tr_b16 v[72:73], v176 offset:1536
	ds_read_b64_tr_b16 v[74:75], v178 offset:1536
	ds_read_b64_tr_b16 v[68:69], v177 offset:1536
	ds_read_b64_tr_b16 v[70:71], v179 offset:1536
	s_waitcnt lgkmcnt(0)
	s_nop 0
	v_mfma_f32_16x16x32_bf16 v[72:75], v[48:51], v[72:75], v[92:95]
	s_nop 2
	ds_read_b128 v[92:95], v182 offset:160
	v_mfma_f32_16x16x32_bf16 v[60:63], v[48:51], v[68:71], v[60:63]
	ds_read_b128 v[68:71], v182 offset:176
	v_mfma_f32_16x16x32_bf16 v[56:59], v[48:51], v[128:131], v[56:59]
	s_waitcnt lgkmcnt(0)
	v_lshl_add_u32 v128, v68, 10, v252
	v_mfma_f32_16x16x32_bf16 v[52:55], v[48:51], v[124:127], v[52:55]
	v_lshl_add_u32 v124, v95, 10, v252
	v_mfma_f32_16x16x32_bf16 v[120:123], v[48:51], v[120:123], v[44:47]
	v_lshl_add_u32 v130, v69, 10, v252
	v_mov_b32_e32 v68, v130
	s_nop 0
	v_lshl_add_u32 v44, v92, 10, v252
	v_lshl_add_u32 v46, v93, 10, v252
	v_lshl_add_u32 v92, v94, 10, v252
	v_mfma_f32_16x16x32_bf16 v[84:87], v[48:51], v[152:155], v[84:87]
	v_mfma_f32_16x16x32_bf16 v[80:83], v[48:51], v[148:151], v[80:83]
	v_mfma_f32_16x16x32_bf16 v[76:79], v[48:51], v[144:147], v[76:79]
	v_mov_b32_e32 v48, v46
	global_load_dwordx4 v[44:47], v44, s[100:101]
	s_nop 0
	global_load_dwordx4 v[48:51], v48, s[100:101]
	s_nop 0
	global_load_dwordx4 v[92:95], v92, s[100:101]
	s_nop 0
	global_load_dwordx4 v[124:127], v124, s[100:101]
	s_nop 0
	global_load_dwordx4 v[128:131], v128, s[100:101]
	s_nop 0
	global_load_dwordx4 v[144:147], v68, s[100:101]
	v_lshl_add_u32 v68, v70, 10, v252
	v_lshl_add_u32 v148, v71, 10, v252
	global_load_dwordx4 v[68:71], v68, s[100:101]
	s_nop 0
	global_load_dwordx4 v[148:151], v148, s[100:101]
	s_waitcnt vmcnt(23)
	ds_write_b128 v236, v[64:67]
	s_waitcnt vmcnt(22)
	ds_write_b128 v236, v[88:91] offset:64
	s_waitcnt vmcnt(21)
	ds_write_b128 v236, v[156:159] offset:128
	s_waitcnt vmcnt(20)
	ds_write_b128 v236, v[168:171] offset:192
	s_waitcnt vmcnt(19)
	ds_write_b128 v237, v[240:243] offset:256
	s_waitcnt vmcnt(18)
	ds_write_b128 v237, v[244:247] offset:320
	s_waitcnt vmcnt(17)
	ds_write_b128 v237, v[164:167] offset:384
	s_waitcnt vmcnt(16)
; #define LAS __attribute__((address_space(3)))
; #define ATT_FENCE() asm volatile("" ::: "memory")
; #define ATT_PV(nt_, ra_, rb_) acc[nt_] = __builtin_amdgcn_mfma_f32_16x16x32_bf16(pa[ch], __builtin_bit_cast(bf16x8, (v4u){ra_.x, ra_.y, rb_.x, rb_.y}), acc[nt_], 0, 0, 0)
; DI void attn_worker(unsigned char* ws, LAS unsigned char* lds, LAS unsigned* qctr, int wave) {
;     ...
;         for (int ch = 0; ch < 8; ++ch) {
;             if (ch + 2 < 8) { const int c2 = (ch + 2) % 3;
;                 ix[c2][0] = *(const LAS v4i*)(idl + 64 * kg + 8 * (ch + 2)); ix[c2][1] = *(const LAS v4i*)(idl + 64 * kg + 8 * (ch + 2) + 4);
; #pragma unroll
;                 for (int j = 0; j < 8; ++j) vv[c2][j] = *(const v4u*)(vbase + (size_t)ix[c2][j >> 2][j & 3] * KVD);
;                 ATT_FENCE(); }
; #pragma unroll
;             for (int j = 0; j < 8; ++j) *(LAS v4u*)(size_t)(vwb[j >> 2] + 64 * j) = vv[ch % 3][j];
;             v2u r0, r1, r2, r3, r4, r5, r6, r7, r8, r9, r10, r11, r12, r13, r14, r15;
;             asm volatile("ds_read_b64_tr_b16 %0, %16\n\tds_read_b64_tr_b16 %1, %18\n\tds_read_b64_tr_b16 %2, %17\n\tds_read_b64_tr_b16 %3, %19\n\t"
;                          "ds_read_b64_tr_b16 %4, %16 offset:512\n\tds_read_b64_tr_b16 %5, %18 offset:512\n\tds_read_b64_tr_b16 %6, %17 offset:512\n\tds_read_b64_tr_b16 %7, %19 offset:512\n\t"
;                          "ds_read_b64_tr_b16 %8, %16 offset:1024\n\tds_read_b64_tr_b16 %9, %18 offset:1024\n\tds_read_b64_tr_b16 %10, %17 offset:1024\n\tds_read_b64_tr_b16 %11, %19 offset:1024\n\t"
;                          "ds_read_b64_tr_b16 %12, %16 offset:1536\n\tds_read_b64_tr_b16 %13, %18 offset:1536\n\tds_read_b64_tr_b16 %14, %17 offset:1536\n\tds_read_b64_tr_b16 %15, %19 offset:1536\n\ts_waitcnt lgkmcnt(0)"
;                          : "=&v"(r0), "=&v"(r1), "=&v"(r2), "=&v"(r3), "=&v"(r4), "=&v"(r5), "=&v"(r6), "=&v"(r7), "=&v"(r8), "=&v"(r9), "=&v"(r10), "=&v"(r11), "=&v"(r12), "=&v"(r13), "=&v"(r14), "=&v"(r15)
;                          : "v"(vtb[0][0]), "v"(vtb[0][1]), "v"(vtb[1][0]), "v"(vtb[1][1]) : "memory");
;     ...
;             ATT_PV(0, r0, r1); ATT_PV(1, r2, r3); ATT_PV(2, r4, r5); ATT_PV(3, r6, r7); ATT_PV(4, r8, r9); ATT_PV(5, r10, r11); ATT_PV(6, r12, r13); ATT_PV(7, r14, r15);
	ds_write_b128 v237, v[248:251] offset:448
	ds_read_b64_tr_b16 v[240:241], v176
	ds_read_b64_tr_b16 v[242:243], v178
	ds_read_b64_tr_b16 v[168:169], v177
	ds_read_b64_tr_b16 v[170:171], v179
	ds_read_b64_tr_b16 v[164:165], v176 offset:512
	ds_read_b64_tr_b16 v[166:167], v178 offset:512
	ds_read_b64_tr_b16 v[160:161], v177 offset:512
	ds_read_b64_tr_b16 v[162:163], v179 offset:512
	ds_read_b64_tr_b16 v[156:157], v176 offset:1024
	ds_read_b64_tr_b16 v[158:159], v178 offset:1024
	ds_read_b64_tr_b16 v[152:153], v177 offset:1024
	ds_read_b64_tr_b16 v[154:155], v179 offset:1024
	ds_read_b64_tr_b16 v[88:89], v176 offset:1536
	ds_read_b64_tr_b16 v[90:91], v178 offset:1536
	ds_read_b64_tr_b16 v[64:65], v177 offset:1536
	ds_read_b64_tr_b16 v[66:67], v179 offset:1536
	s_waitcnt lgkmcnt(0)
	s_nop 0
	v_mfma_f32_16x16x32_bf16 v[72:75], v[36:39], v[88:91], v[72:75]
	ds_read_b128 v[88:91], v182 offset:192
	v_mfma_f32_16x16x32_bf16 v[84:87], v[36:39], v[240:243], v[84:87]
	v_mfma_f32_16x16x32_bf16 v[80:83], v[36:39], v[168:171], v[80:83]
	v_mfma_f32_16x16x32_bf16 v[76:79], v[36:39], v[164:167], v[76:79]
	v_mfma_f32_16x16x32_bf16 v[56:59], v[36:39], v[160:163], v[56:59]
	v_mfma_f32_16x16x32_bf16 v[52:55], v[36:39], v[156:159], v[52:55]
	v_mfma_f32_16x16x32_bf16 v[120:123], v[36:39], v[152:155], v[120:123]
	v_mfma_f32_16x16x32_bf16 v[36:39], v[36:39], v[64:67], v[60:63]
	s_nop 2
	ds_read_b128 v[60:63], v182 offset:208
	s_waitcnt lgkmcnt(1)
	v_lshl_add_u32 v64, v88, 10, v252
	v_lshl_add_u32 v66, v89, 10, v252
	v_mov_b32_e32 v88, v66
	global_load_dwordx4 v[64:67], v64, s[100:101]
	s_nop 0
	global_load_dwordx4 v[152:155], v88, s[100:101]
	v_lshl_add_u32 v88, v90, 10, v252
	v_lshl_add_u32 v156, v91, 10, v252
	s_waitcnt lgkmcnt(0)
	v_lshl_add_u32 v160, v60, 10, v252
	v_lshl_add_u32 v162, v61, 10, v252
	v_mov_b32_e32 v60, v162
	global_load_dwordx4 v[88:91], v88, s[100:101]
	s_nop 0
	global_load_dwordx4 v[156:159], v156, s[100:101]
	s_nop 0
	global_load_dwordx4 v[160:163], v160, s[100:101]
	s_nop 0
	global_load_dwordx4 v[164:167], v60, s[100:101]
	v_lshl_add_u32 v60, v62, 10, v252
	v_lshl_add_u32 v168, v63, 10, v252
	global_load_dwordx4 v[60:63], v60, s[100:101]
	s_nop 0
	global_load_dwordx4 v[168:171], v168, s[100:101]
	s_waitcnt vmcnt(23)
	ds_write_b128 v236, v[24:27]
	s_waitcnt vmcnt(22)
	ds_write_b128 v236, v[40:43] offset:64
	s_waitcnt vmcnt(21)
	ds_write_b128 v236, v[96:99] offset:128
	s_waitcnt vmcnt(20)
	ds_write_b128 v236, v[104:107] offset:192
	s_waitcnt vmcnt(19)
	ds_write_b128 v237, v[108:111] offset:256
	s_waitcnt vmcnt(18)
	ds_write_b128 v237, v[112:115] offset:320
	s_waitcnt vmcnt(17)
	ds_write_b128 v237, v[100:103] offset:384
	s_waitcnt vmcnt(16)
	ds_write_b128 v237, v[116:119] offset:448
	ds_read_b64_tr_b16 v[116:117], v176
	ds_read_b64_tr_b16 v[118:119], v178
	ds_read_b64_tr_b16 v[112:113], v177
	ds_read_b64_tr_b16 v[114:115], v179
	ds_read_b64_tr_b16 v[108:109], v176 offset:512
	ds_read_b64_tr_b16 v[110:111], v178 offset:512
	ds_read_b64_tr_b16 v[104:105], v177 offset:512
	ds_read_b64_tr_b16 v[106:107], v179 offset:512
	ds_read_b64_tr_b16 v[100:101], v176 offset:1024
	ds_read_b64_tr_b16 v[102:103], v178 offset:1024
	ds_read_b64_tr_b16 v[96:97], v177 offset:1024
	ds_read_b64_tr_b16 v[98:99], v179 offset:1024
	ds_read_b64_tr_b16 v[40:41], v176 offset:1536
	ds_read_b64_tr_b16 v[42:43], v178 offset:1536
	ds_read_b64_tr_b16 v[24:25], v177 offset:1536
	ds_read_b64_tr_b16 v[26:27], v179 offset:1536
	s_waitcnt lgkmcnt(0)
	s_nop 0
	v_mfma_f32_16x16x32_bf16 v[40:43], v[32:35], v[40:43], v[72:75]
	s_nop 2
	ds_read_b128 v[72:75], v182 offset:224
	v_mfma_f32_16x16x32_bf16 v[84:87], v[32:35], v[116:119], v[84:87]
	v_mfma_f32_16x16x32_bf16 v[80:83], v[32:35], v[112:115], v[80:83]
	v_mfma_f32_16x16x32_bf16 v[76:79], v[32:35], v[108:111], v[76:79]
	v_mfma_f32_16x16x32_bf16 v[56:59], v[32:35], v[104:107], v[56:59]
	v_mfma_f32_16x16x32_bf16 v[52:55], v[32:35], v[100:103], v[52:55]
	v_mfma_f32_16x16x32_bf16 v[96:99], v[32:35], v[96:99], v[120:123]
	v_mfma_f32_16x16x32_bf16 v[24:27], v[32:35], v[24:27], v[36:39]
	ds_read_b128 v[32:35], v182 offset:240
	s_waitcnt lgkmcnt(1)
	v_lshl_add_u32 v104, v75, 10, v252
	v_lshl_add_u32 v36, v72, 10, v252
	v_lshl_add_u32 v38, v73, 10, v252
	v_mov_b32_e32 v72, v38
	global_load_dwordx4 v[36:39], v36, s[100:101]
	s_nop 0
	global_load_dwordx4 v[100:103], v72, s[100:101]
	v_lshl_add_u32 v72, v74, 10, v252
	s_waitcnt lgkmcnt(0)
	v_lshl_add_u32 v108, v32, 10, v252
	v_lshl_add_u32 v110, v33, 10, v252
	v_mov_b32_e32 v32, v110
	global_load_dwordx4 v[72:75], v72, s[100:101]
	s_nop 0
	global_load_dwordx4 v[104:107], v104, s[100:101]
	s_nop 0
	global_load_dwordx4 v[108:111], v108, s[100:101]
	s_nop 0
	global_load_dwordx4 v[112:115], v32, s[100:101]
	v_lshl_add_u32 v32, v34, 10, v252
	v_lshl_add_u32 v116, v35, 10, v252
	global_load_dwordx4 v[32:35], v32, s[100:101]
	s_nop 0
	global_load_dwordx4 v[116:119], v116, s[100:101]
	s_waitcnt vmcnt(23)
	ds_write_b128 v236, v[44:47]
	s_waitcnt vmcnt(22)
	ds_write_b128 v236, v[48:51] offset:64
	s_waitcnt vmcnt(21)
	ds_write_b128 v236, v[92:95] offset:128
	s_waitcnt vmcnt(20)
	ds_write_b128 v236, v[124:127] offset:192
	s_waitcnt vmcnt(19)
	ds_write_b128 v237, v[128:131] offset:256
	s_waitcnt vmcnt(18)
	ds_write_b128 v237, v[144:147] offset:320
	s_waitcnt vmcnt(17)
	ds_write_b128 v237, v[68:71] offset:384
	s_waitcnt vmcnt(16)
; #define LAS __attribute__((address_space(3)))
; #define ATT_FENCE() asm volatile("" ::: "memory")
; #define ATT_PV(nt_, ra_, rb_) acc[nt_] = __builtin_amdgcn_mfma_f32_16x16x32_bf16(pa[ch], __builtin_bit_cast(bf16x8, (v4u){ra_.x, ra_.y, rb_.x, rb_.y}), acc[nt_], 0, 0, 0)
; DI void attn_worker(unsigned char* ws, LAS unsigned char* lds, LAS unsigned* qctr, int wave) {
;     ...
;         for (int ch = 0; ch < 8; ++ch) {
;             if (ch + 2 < 8) { const int c2 = (ch + 2) % 3;
;                 ix[c2][0] = *(const LAS v4i*)(idl + 64 * kg + 8 * (ch + 2)); ix[c2][1] = *(const LAS v4i*)(idl + 64 * kg + 8 * (ch + 2) + 4);
; #pragma unroll
;                 for (int j = 0; j < 8; ++j) vv[c2][j] = *(const v4u*)(vbase + (size_t)ix[c2][j >> 2][j & 3] * KVD);
;                 ATT_FENCE(); }
; #pragma unroll
;             for (int j = 0; j < 8; ++j) *(LAS v4u*)(size_t)(vwb[j >> 2] + 64 * j) = vv[ch % 3][j];
;             v2u r0, r1, r2, r3, r4, r5, r6, r7, r8, r9, r10, r11, r12, r13, r14, r15;
;             asm volatile("ds_read_b64_tr_b16 %0, %16\n\tds_read_b64_tr_b16 %1, %18\n\tds_read_b64_tr_b16 %2, %17\n\tds_read_b64_tr_b16 %3, %19\n\t"
;                          "ds_read_b64_tr_b16 %4, %16 offset:512\n\tds_read_b64_tr_b16 %5, %18 offset:512\n\tds_read_b64_tr_b16 %6, %17 offset:512\n\tds_read_b64_tr_b16 %7, %19 offset:512\n\t"
;                          "ds_read_b64_tr_b16 %8, %16 offset:1024\n\tds_read_b64_tr_b16 %9, %18 offset:1024\n\tds_read_b64_tr_b16 %10, %17 offset:1024\n\tds_read_b64_tr_b16 %11, %19 offset:1024\n\t"
;                          "ds_read_b64_tr_b16 %12, %16 offset:1536\n\tds_read_b64_tr_b16 %13, %18 offset:1536\n\tds_read_b64_tr_b16 %14, %17 offset:1536\n\tds_read_b64_tr_b16 %15, %19 offset:1536\n\ts_waitcnt lgkmcnt(0)"
;                          : "=&v"(r0), "=&v"(r1), "=&v"(r2), "=&v"(r3), "=&v"(r4), "=&v"(r5), "=&v"(r6), "=&v"(r7), "=&v"(r8), "=&v"(r9), "=&v"(r10), "=&v"(r11), "=&v"(r12), "=&v"(r13), "=&v"(r14), "=&v"(r15)
;                          : "v"(vtb[0][0]), "v"(vtb[0][1]), "v"(vtb[1][0]), "v"(vtb[1][1]) : "memory");
;     ...
;             ATT_PV(0, r0, r1); ATT_PV(1, r2, r3); ATT_PV(2, r4, r5); ATT_PV(3, r6, r7); ATT_PV(4, r8, r9); ATT_PV(5, r10, r11); ATT_PV(6, r12, r13); ATT_PV(7, r14, r15);
;     ...
;         }
	ds_write_b128 v237, v[148:151] offset:448
	ds_read_b64_tr_b16 v[144:145], v176
	ds_read_b64_tr_b16 v[146:147], v178
	ds_read_b64_tr_b16 v[128:129], v177
	ds_read_b64_tr_b16 v[130:131], v179
	ds_read_b64_tr_b16 v[124:125], v176 offset:512
	ds_read_b64_tr_b16 v[126:127], v178 offset:512
	ds_read_b64_tr_b16 v[120:121], v177 offset:512
	ds_read_b64_tr_b16 v[122:123], v179 offset:512
	ds_read_b64_tr_b16 v[92:93], v176 offset:1024
	ds_read_b64_tr_b16 v[94:95], v178 offset:1024
	ds_read_b64_tr_b16 v[68:69], v177 offset:1024
	ds_read_b64_tr_b16 v[70:71], v179 offset:1024
	ds_read_b64_tr_b16 v[48:49], v176 offset:1536
	ds_read_b64_tr_b16 v[50:51], v178 offset:1536
	ds_read_b64_tr_b16 v[44:45], v177 offset:1536
	ds_read_b64_tr_b16 v[46:47], v179 offset:1536
	s_waitcnt lgkmcnt(0)
	s_waitcnt vmcnt(15)
	ds_write_b128 v236, v[64:67]
	s_waitcnt vmcnt(14)
	ds_write_b128 v236, v[152:155] offset:64
	s_waitcnt vmcnt(13)
	ds_write_b128 v236, v[88:91] offset:128
	s_waitcnt vmcnt(12)
	ds_write_b128 v236, v[156:159] offset:192
	s_waitcnt vmcnt(11)
	ds_write_b128 v237, v[160:163] offset:256
	s_waitcnt vmcnt(10)
	ds_write_b128 v237, v[164:167] offset:320
	s_waitcnt vmcnt(9)
	ds_write_b128 v237, v[60:63] offset:384
	s_waitcnt vmcnt(8)
	ds_write_b128 v237, v[168:171] offset:448
	v_mfma_f32_16x16x32_bf16 v[84:87], v[28:31], v[144:147], v[84:87]
	v_mfma_f32_16x16x32_bf16 v[80:83], v[28:31], v[128:131], v[80:83]
	v_mfma_f32_16x16x32_bf16 v[76:79], v[28:31], v[124:127], v[76:79]
	v_mfma_f32_16x16x32_bf16 v[56:59], v[28:31], v[120:123], v[56:59]
	v_mfma_f32_16x16x32_bf16 v[52:55], v[28:31], v[92:95], v[52:55]
	v_mfma_f32_16x16x32_bf16 v[68:71], v[28:31], v[68:71], v[96:99]
	v_mfma_f32_16x16x32_bf16 v[40:43], v[28:31], v[48:51], v[40:43]
	v_mfma_f32_16x16x32_bf16 v[24:27], v[28:31], v[44:47], v[24:27]
	ds_read_b64_tr_b16 v[96:97], v176
	ds_read_b64_tr_b16 v[98:99], v178
	ds_read_b64_tr_b16 v[92:93], v177
	ds_read_b64_tr_b16 v[94:95], v179
	ds_read_b64_tr_b16 v[88:89], v176 offset:512
	ds_read_b64_tr_b16 v[90:91], v178 offset:512
	ds_read_b64_tr_b16 v[64:65], v177 offset:512
	ds_read_b64_tr_b16 v[66:67], v179 offset:512
	ds_read_b64_tr_b16 v[60:61], v176 offset:1024
	ds_read_b64_tr_b16 v[62:63], v178 offset:1024
	ds_read_b64_tr_b16 v[48:49], v177 offset:1024
	ds_read_b64_tr_b16 v[50:51], v179 offset:1024
	ds_read_b64_tr_b16 v[44:45], v176 offset:1536
	ds_read_b64_tr_b16 v[46:47], v178 offset:1536
	ds_read_b64_tr_b16 v[28:29], v177 offset:1536
	ds_read_b64_tr_b16 v[30:31], v179 offset:1536
	s_waitcnt lgkmcnt(0)
	s_waitcnt vmcnt(7)
	ds_write_b128 v236, v[36:39]
	s_waitcnt vmcnt(6)
	ds_write_b128 v236, v[100:103] offset:64
	s_waitcnt vmcnt(5)
	ds_write_b128 v236, v[72:75] offset:128
	s_waitcnt vmcnt(4)
	ds_write_b128 v236, v[104:107] offset:192
	s_waitcnt vmcnt(3)
	ds_write_b128 v237, v[108:111] offset:256
	s_waitcnt vmcnt(2)
	ds_write_b128 v237, v[112:115] offset:320
	s_waitcnt vmcnt(1)
	ds_write_b128 v237, v[32:35] offset:384
	s_waitcnt vmcnt(0)
	ds_write_b128 v237, v[116:119] offset:448
	v_mfma_f32_16x16x32_bf16 v[84:87], v[20:23], v[96:99], v[84:87]
	v_mfma_f32_16x16x32_bf16 v[80:83], v[20:23], v[92:95], v[80:83]
	v_mfma_f32_16x16x32_bf16 v[76:79], v[20:23], v[88:91], v[76:79]
	v_mfma_f32_16x16x32_bf16 v[56:59], v[20:23], v[64:67], v[56:59]
	v_mfma_f32_16x16x32_bf16 v[52:55], v[20:23], v[60:63], v[52:55]
	v_mfma_f32_16x16x32_bf16 v[48:51], v[20:23], v[48:51], v[68:71]
	v_mfma_f32_16x16x32_bf16 v[60:63], v[20:23], v[44:47], v[40:43]
	v_mfma_f32_16x16x32_bf16 v[64:67], v[20:23], v[28:31], v[24:27]
	ds_read_b64_tr_b16 v[44:45], v176
	ds_read_b64_tr_b16 v[46:47], v178
	ds_read_b64_tr_b16 v[40:41], v177
	ds_read_b64_tr_b16 v[42:43], v179
	ds_read_b64_tr_b16 v[36:37], v176 offset:512
	ds_read_b64_tr_b16 v[38:39], v178 offset:512
	ds_read_b64_tr_b16 v[32:33], v177 offset:512
	ds_read_b64_tr_b16 v[34:35], v179 offset:512
	ds_read_b64_tr_b16 v[28:29], v176 offset:1024
	ds_read_b64_tr_b16 v[30:31], v178 offset:1024
	ds_read_b64_tr_b16 v[24:25], v177 offset:1024
	ds_read_b64_tr_b16 v[26:27], v179 offset:1024
	ds_read_b64_tr_b16 v[20:21], v176 offset:1536
	ds_read_b64_tr_b16 v[22:23], v178 offset:1536
	ds_read_b64_tr_b16 v[68:69], v177 offset:1536
	ds_read_b64_tr_b16 v[70:71], v179 offset:1536
	s_waitcnt lgkmcnt(0)
	s_nop 0
	v_mfma_f32_16x16x32_bf16 v[44:47], v[16:19], v[44:47], v[84:87]
	v_mfma_f32_16x16x32_bf16 v[40:43], v[16:19], v[40:43], v[80:83]
	v_mfma_f32_16x16x32_bf16 v[36:39], v[16:19], v[36:39], v[76:79]
	v_mfma_f32_16x16x32_bf16 v[32:35], v[16:19], v[32:35], v[56:59]
	v_mfma_f32_16x16x32_bf16 v[28:31], v[16:19], v[28:31], v[52:55]
	v_mfma_f32_16x16x32_bf16 v[24:27], v[16:19], v[24:27], v[48:51]
	v_mfma_f32_16x16x32_bf16 v[20:23], v[16:19], v[20:23], v[60:63]
	v_mfma_f32_16x16x32_bf16 v[16:19], v[16:19], v[68:71], v[64:67]
	s_mov_b64 s[0:1], exec
	v_readlane_b32 s2, v253, 5
	v_readlane_b32 s3, v253, 6
	s_and_b64 s[2:3], s[0:1], s[2:3]
	s_mov_b64 exec, s[2:3]
	s_cbranch_execz .LBB0_2273
; #define LAS __attribute__((address_space(3)))
; DI unsigned f2bf(float f) { unsigned u = __builtin_bit_cast(unsigned, f); return (u + 0x7fffu + ((u >> 16) & 1u)) >> 16; }
; DI void attn_worker(unsigned char* ws, LAS unsigned char* lds, LAS unsigned* qctr, int wave) {
;     ...
;         { LAS unsigned short* ob = (LAS unsigned short*)(lds + 2048);
;           if (lane < 16) {
; #pragma unroll
;             for (int nt = 0; nt < 8; ++nt)
; #pragma unroll
;                 for (int e = 0; e < 4; ++e) ob[e * 128 + 16 * nt + lane] = f2bf(acc[nt][e]); }
	v_bfe_u32 v48, v44, 16, 1
	v_add3_u32 v44, v44, v48, s79
	ds_write_b16_d16_hi v238, v44 offset:2048
	v_bfe_u32 v44, v45, 16, 1
	v_add3_u32 v44, v45, v44, s79
	ds_write_b16_d16_hi v238, v44 offset:2304
	v_bfe_u32 v44, v46, 16, 1
	v_add3_u32 v44, v46, v44, s79
	ds_write_b16_d16_hi v238, v44 offset:2560
	v_bfe_u32 v44, v47, 16, 1
	v_add3_u32 v44, v47, v44, s79
	ds_write_b16_d16_hi v238, v44 offset:2816
	v_bfe_u32 v44, v40, 16, 1
	v_add3_u32 v40, v40, v44, s79
	ds_write_b16_d16_hi v238, v40 offset:2080
	v_bfe_u32 v40, v41, 16, 1
	v_add3_u32 v40, v41, v40, s79
	ds_write_b16_d16_hi v238, v40 offset:2336
	v_bfe_u32 v40, v42, 16, 1
	v_add3_u32 v40, v42, v40, s79
	ds_write_b16_d16_hi v238, v40 offset:2592
	v_bfe_u32 v40, v43, 16, 1
	v_add3_u32 v40, v43, v40, s79
	ds_write_b16_d16_hi v238, v40 offset:2848
	v_bfe_u32 v40, v36, 16, 1
	v_add3_u32 v36, v36, v40, s79
	ds_write_b16_d16_hi v238, v36 offset:2112
	v_bfe_u32 v36, v37, 16, 1
	v_add3_u32 v36, v37, v36, s79
	ds_write_b16_d16_hi v238, v36 offset:2368
	v_bfe_u32 v36, v38, 16, 1
	v_add3_u32 v36, v38, v36, s79
	ds_write_b16_d16_hi v238, v36 offset:2624
	v_bfe_u32 v36, v39, 16, 1
	v_add3_u32 v36, v39, v36, s79
	ds_write_b16_d16_hi v238, v36 offset:2880
	v_bfe_u32 v36, v32, 16, 1
	v_add3_u32 v32, v32, v36, s79
	ds_write_b16_d16_hi v238, v32 offset:2144
	v_bfe_u32 v32, v33, 16, 1
	v_add3_u32 v32, v33, v32, s79
	ds_write_b16_d16_hi v238, v32 offset:2400
	v_bfe_u32 v32, v34, 16, 1
	v_add3_u32 v32, v34, v32, s79
	ds_write_b16_d16_hi v238, v32 offset:2656
	v_bfe_u32 v32, v35, 16, 1
	v_add3_u32 v32, v35, v32, s79
	ds_write_b16_d16_hi v238, v32 offset:2912
	v_bfe_u32 v32, v28, 16, 1
	v_add3_u32 v28, v28, v32, s79
	ds_write_b16_d16_hi v238, v28 offset:2176
	v_bfe_u32 v28, v29, 16, 1
	v_add3_u32 v28, v29, v28, s79
	ds_write_b16_d16_hi v238, v28 offset:2432
	v_bfe_u32 v28, v30, 16, 1
	v_add3_u32 v28, v30, v28, s79
	ds_write_b16_d16_hi v238, v28 offset:2688
	v_bfe_u32 v28, v31, 16, 1
	v_add3_u32 v28, v31, v28, s79
	ds_write_b16_d16_hi v238, v28 offset:2944
	v_bfe_u32 v28, v24, 16, 1
	v_add3_u32 v24, v24, v28, s79
	ds_write_b16_d16_hi v238, v24 offset:2208
	v_bfe_u32 v24, v25, 16, 1
	v_add3_u32 v24, v25, v24, s79
	ds_write_b16_d16_hi v238, v24 offset:2464
	v_bfe_u32 v24, v26, 16, 1
	v_add3_u32 v24, v26, v24, s79
	ds_write_b16_d16_hi v238, v24 offset:2720
	v_bfe_u32 v24, v27, 16, 1
	v_add3_u32 v24, v27, v24, s79
	ds_write_b16_d16_hi v238, v24 offset:2976
	v_bfe_u32 v24, v20, 16, 1
	v_add3_u32 v20, v20, v24, s79
	ds_write_b16_d16_hi v238, v20 offset:2240
	v_bfe_u32 v20, v21, 16, 1
	v_add3_u32 v20, v21, v20, s79
	ds_write_b16_d16_hi v238, v20 offset:2496
	v_bfe_u32 v20, v22, 16, 1
	v_add3_u32 v20, v22, v20, s79
	ds_write_b16_d16_hi v238, v20 offset:2752
	v_bfe_u32 v20, v23, 16, 1
	v_add3_u32 v20, v23, v20, s79
	ds_write_b16_d16_hi v238, v20 offset:3008
	v_bfe_u32 v20, v16, 16, 1
	v_add3_u32 v16, v16, v20, s79
	ds_write_b16_d16_hi v238, v16 offset:2272
	v_bfe_u32 v16, v17, 16, 1
	v_add3_u32 v16, v17, v16, s79
	ds_write_b16_d16_hi v238, v16 offset:2528
	v_bfe_u32 v16, v18, 16, 1
	v_add3_u32 v16, v18, v16, s79
	ds_write_b16_d16_hi v238, v16 offset:2784
	v_bfe_u32 v16, v19, 16, 1
	v_add3_u32 v16, v19, v16, s79
	ds_write_b16_d16_hi v238, v16 offset:3040
	s_branch .LBB0_2273
